# prep: non-temporal hint on the read-once x rows and f32 weight loads (keeps hb / bf16 weights in the memory-side cache); prep temps moved to s54-s59
# speedup vs baseline: 1.0135x; 1.0030x over previous
; __device__ __forceinline__ void tr_item(const float* W, int ldw, int K, int k0, int srccol0, bf16* WT, int dstrow0, const float* gain, float scale, LAS float* scr, int lane, const float* gain2 = nullptr) {
;     ...
;     for (int i = 0; i < 32; ++i) { const int kk = 2 * i + (lane >> 5); float gsc = gain ? gain[k0 + kk] * scale : scale; if (gain2) gsc *= gain2[k0 + kk]; scr[kk * 33 + (lane & 31)] = W[(size_t)(k0 + kk) * ldw + srccol0 + (lane & 31)] * gsc; }
; __device__ __forceinline__ void phase_prep(const Args& a, unsigned char* ws, LAS unsigned char* lds, int vcu, int G, int tid, int wid, int lane) {
;     ...
;     for (int it = gw; it < 2 * I_L; it += NGW) {
;         const int l = it / I_L; int r = it % I_L;
;         unsigned char* wl = ws + WS_W + (size_t)l * W_LAYER;
;         if (r < I_GU || (r >= I_GU + I_D + I_IN + I_OUT && r < 2 * I_GU + I_D + I_IN + I_OUT)) {
;             const bool second = r >= I_GU; if (second) r -= I_GU + I_D + I_IN + I_OUT;
;     ...
;         { const int kb = r / 32, nb = r % 32; tr_item(a.in[19] + (size_t)l * FF * DM, DM, FF, kb * 64, nb * 32, (bf16*)(wl + WO_D2), nb * 32, nullptr, 0.5f, scr, lane); }
.LBB0_14:
	s_mul_hi_i32 s2, s44, 0x30c30c31
	s_lshr_b32 s3, s2, 31
	s_ashr_i32 s2, s2, 11
	s_add_i32 s4, s2, s3
	s_mul_i32 s2, s4, 0xffffd600
	s_add_i32 s47, s44, s2
	s_ashr_i32 s5, s4, 31
	s_mul_i32 s3, s4, 0x2a00000
	s_mul_hi_i32 s2, s4, 0x2a00000
	s_add_u32 s46, s0, s3
	s_addc_u32 s45, s1, s2
	s_cmpk_lt_i32 s47, 0xb00
	s_cselect_b64 s[42:43], -1, 0
	s_add_i32 s48, s47, 0xffffe680
	s_cmpk_lt_u32 s48, 0xb00
	s_cselect_b64 s[2:3], -1, 0
	s_or_b64 s[2:3], s[42:43], s[2:3]
	s_andn2_b64 vcc, exec, s[2:3]
	s_mov_b64 s[2:3], -1
	s_cbranch_vccz .LBB0_80
	s_cmpk_gt_u32 s47, 0x107f
	s_cbranch_scc0 .LBB0_77
	s_cmpk_gt_u32 s47, 0x177f
	s_cbranch_scc0 .LBB0_22
	s_cmpk_gt_u32 s47, 0x197f
	s_cbranch_scc0 .LBB0_19
	s_add_i32 s2, s47, 0xdb80
	s_sext_i32_i16 s3, s2
	s_bfe_u32 s3, s3, 0x5001a
	s_add_i32 s3, s2, s3
	s_sext_i32_i16 s20, s3
	s_and_b32 s3, s3, 0xffe0
	s_sub_i32 s2, s2, s3
	s_mul_i32 s49, s4, 0xb00000
	s_sext_i32_i16 s2, s2
	s_mul_hi_i32 s3, s4, 0xb00000
	s_add_u32 s49, s12, s49
	s_addc_u32 s51, s13, s3
	s_lshl_b32 s3, s20, 1
	s_lshl_b32 s2, s2, 5
	s_and_b32 s50, s3, 0xffffffc0
	s_ashr_i32 s3, s2, 31
	s_lshl_b64 s[52:53], s[2:3], 2
	s_add_u32 s52, s49, s52
	v_or_b32_e32 v12, s50, v2
	v_or_b32_e32 v14, s50, v16
	v_or_b32_e32 v80, s50, v17
	v_or_b32_e32 v82, s50, v19
	v_or_b32_e32 v88, s50, v23
	s_addc_u32 s53, s51, s53
	v_lshlrev_b32_e32 v6, 2, v4
	v_ashrrev_i32_e32 v13, 31, v12
	v_ashrrev_i32_e32 v15, 31, v14
	v_ashrrev_i32_e32 v81, 31, v80
	v_ashrrev_i32_e32 v83, 31, v82
	v_or_b32_e32 v84, s50, v20
	v_or_b32_e32 v86, s50, v22
	v_ashrrev_i32_e32 v89, 31, v88
	v_or_b32_e32 v90, s50, v25
	v_lshl_add_u64 v[10:11], s[52:53], 0, v[6:7]
	v_lshlrev_b64 v[12:13], 12, v[12:13]
	v_lshlrev_b64 v[14:15], 12, v[14:15]
	v_lshlrev_b64 v[80:81], 12, v[80:81]
	v_lshlrev_b64 v[82:83], 12, v[82:83]
	v_ashrrev_i32_e32 v85, 31, v84
	v_ashrrev_i32_e32 v87, 31, v86
	v_lshlrev_b64 v[88:89], 12, v[88:89]
	v_ashrrev_i32_e32 v91, 31, v90
	v_lshl_add_u64 v[12:13], v[10:11], 0, v[12:13]
	v_lshl_add_u64 v[14:15], v[10:11], 0, v[14:15]
	v_lshl_add_u64 v[80:81], v[10:11], 0, v[80:81]
	v_lshl_add_u64 v[82:83], v[10:11], 0, v[82:83]
	v_lshlrev_b64 v[84:85], 12, v[84:85]
	v_lshlrev_b64 v[86:87], 12, v[86:87]
	v_lshl_add_u64 v[88:89], v[10:11], 0, v[88:89]
	v_lshlrev_b64 v[90:91], 12, v[90:91]
	v_lshl_add_u64 v[84:85], v[10:11], 0, v[84:85]
	v_lshl_add_u64 v[86:87], v[10:11], 0, v[86:87]
	v_lshl_add_u64 v[90:91], v[10:11], 0, v[90:91]
	global_load_dword v6, v[12:13], off nt
	global_load_dword v79, v[14:15], off nt
	global_load_dword v92, v[80:81], off nt
	global_load_dword v93, v[82:83], off nt
	global_load_dword v94, v[84:85], off nt
	global_load_dword v95, v[86:87], off nt
	global_load_dword v96, v[88:89], off nt
	global_load_dword v97, v[90:91], off nt
	v_or_b32_e32 v12, s50, v26
	v_or_b32_e32 v14, s50, v28
	v_or_b32_e32 v80, s50, v29
	v_or_b32_e32 v82, s50, v31
	v_or_b32_e32 v88, s50, v35
	v_ashrrev_i32_e32 v13, 31, v12
	v_ashrrev_i32_e32 v15, 31, v14
	v_ashrrev_i32_e32 v81, 31, v80
	v_ashrrev_i32_e32 v83, 31, v82
	v_or_b32_e32 v84, s50, v32
	v_or_b32_e32 v86, s50, v34
	v_ashrrev_i32_e32 v89, 31, v88
	v_or_b32_e32 v90, s50, v37
	v_lshlrev_b64 v[12:13], 12, v[12:13]
	v_lshlrev_b64 v[14:15], 12, v[14:15]
	v_lshlrev_b64 v[80:81], 12, v[80:81]
	v_lshlrev_b64 v[82:83], 12, v[82:83]
	v_ashrrev_i32_e32 v85, 31, v84
	v_ashrrev_i32_e32 v87, 31, v86
	v_lshlrev_b64 v[88:89], 12, v[88:89]
	v_ashrrev_i32_e32 v91, 31, v90
	v_lshl_add_u64 v[12:13], v[10:11], 0, v[12:13]
	v_lshl_add_u64 v[14:15], v[10:11], 0, v[14:15]
	v_lshl_add_u64 v[80:81], v[10:11], 0, v[80:81]
	v_lshl_add_u64 v[82:83], v[10:11], 0, v[82:83]
	v_lshlrev_b64 v[84:85], 12, v[84:85]
	v_lshlrev_b64 v[86:87], 12, v[86:87]
	v_lshl_add_u64 v[88:89], v[10:11], 0, v[88:89]
	v_lshlrev_b64 v[90:91], 12, v[90:91]
	v_lshl_add_u64 v[84:85], v[10:11], 0, v[84:85]
	v_lshl_add_u64 v[86:87], v[10:11], 0, v[86:87]
	v_lshl_add_u64 v[90:91], v[10:11], 0, v[90:91]
	global_load_dword v98, v[12:13], off nt
	global_load_dword v99, v[14:15], off nt
	global_load_dword v100, v[80:81], off nt
	global_load_dword v101, v[82:83], off nt
	global_load_dword v102, v[84:85], off nt
	global_load_dword v103, v[86:87], off nt
	global_load_dword v104, v[88:89], off nt
	global_load_dword v105, v[90:91], off nt
	v_or_b32_e32 v12, s50, v38
	v_or_b32_e32 v14, s50, v40
	v_or_b32_e32 v80, s50, v41
	v_or_b32_e32 v82, s50, v43
	v_or_b32_e32 v88, s50, v63
	v_ashrrev_i32_e32 v13, 31, v12
	v_ashrrev_i32_e32 v15, 31, v14
	v_ashrrev_i32_e32 v81, 31, v80
	v_ashrrev_i32_e32 v83, 31, v82
	v_or_b32_e32 v84, s50, v61
	v_or_b32_e32 v86, s50, v62
	v_ashrrev_i32_e32 v89, 31, v88
	v_or_b32_e32 v90, s50, v64
	v_lshlrev_b64 v[12:13], 12, v[12:13]
	v_lshlrev_b64 v[14:15], 12, v[14:15]
	v_lshlrev_b64 v[80:81], 12, v[80:81]
	v_lshlrev_b64 v[82:83], 12, v[82:83]
	v_ashrrev_i32_e32 v85, 31, v84
	v_ashrrev_i32_e32 v87, 31, v86
	v_lshlrev_b64 v[88:89], 12, v[88:89]
	v_ashrrev_i32_e32 v91, 31, v90
	v_lshl_add_u64 v[12:13], v[10:11], 0, v[12:13]
	v_lshl_add_u64 v[14:15], v[10:11], 0, v[14:15]
	v_lshl_add_u64 v[80:81], v[10:11], 0, v[80:81]
	v_lshl_add_u64 v[82:83], v[10:11], 0, v[82:83]
	v_lshlrev_b64 v[84:85], 12, v[84:85]
	v_lshlrev_b64 v[86:87], 12, v[86:87]
	v_lshl_add_u64 v[88:89], v[10:11], 0, v[88:89]
	v_lshlrev_b64 v[90:91], 12, v[90:91]
	v_lshl_add_u64 v[84:85], v[10:11], 0, v[84:85]
	v_lshl_add_u64 v[86:87], v[10:11], 0, v[86:87]
	v_lshl_add_u64 v[90:91], v[10:11], 0, v[90:91]
	global_load_dword v106, v[12:13], off nt
	global_load_dword v107, v[14:15], off nt
	global_load_dword v108, v[80:81], off nt
	global_load_dword v109, v[82:83], off nt
	global_load_dword v110, v[84:85], off nt
; #define LAS __attribute__((address_space(3)))
; #define LDS_WAIT() asm volatile("s_waitcnt lgkmcnt(0)" ::: "memory")
; __device__ __forceinline__ unsigned pkbf(float lo, float hi) { typedef __bf16 bf2_t __attribute__((ext_vector_type(2))); f32x2 v = {lo, hi}; bf2_t b = __builtin_convertvector(v, bf2_t); return __builtin_bit_cast(unsigned, b); }
; __device__ __forceinline__ void tr_item(const float* W, int ldw, int K, int k0, int srccol0, bf16* WT, int dstrow0, const float* gain, float scale, LAS float* scr, int lane, const float* gain2 = nullptr) {
;     ...
;     for (int i = 0; i < 32; ++i) { const int kk = 2 * i + (lane >> 5); float gsc = gain ? gain[k0 + kk] * scale : scale; if (gain2) gsc *= gain2[k0 + kk]; scr[kk * 33 + (lane & 31)] = W[(size_t)(k0 + kk) * ldw + srccol0 + (lane & 31)] * gsc; }
;     LDS_WAIT();
;     const int c = lane & 7;
; #pragma unroll
;     for (int j = 0; j < 4; ++j) { const int n = (lane >> 3) + 8 * j; const LAS float* s = scr + (8 * c) * 33 + n;
;         u32x4 o; o.x = pkbf(s[0 * 33], s[1 * 33]); o.y = pkbf(s[2 * 33], s[3 * 33]); o.z = pkbf(s[4 * 33], s[5 * 33]); o.w = pkbf(s[6 * 33], s[7 * 33]);
;         *(u32x4*)(WT + (size_t)(dstrow0 + n) * K + k0 + 8 * c) = o; }
;     LDS_WAIT();
; __device__ __forceinline__ void phase_prep(const Args& a, unsigned char* ws, LAS unsigned char* lds, int vcu, int G, int tid, int wid, int lane) {
;     ...
;         { const int kb = r / 32, nb = r % 32; tr_item(a.in[19] + (size_t)l * FF * DM, DM, FF, kb * 64, nb * 32, (bf16*)(wl + WO_D2), nb * 32, nullptr, 0.5f, scr, lane); }
	global_load_dword v111, v[86:87], off nt
	s_nop 0
	global_load_dword v88, v[88:89], off nt
	s_nop 0
	global_load_dword v89, v[90:91], off nt
	v_or_b32_e32 v12, s50, v65
	v_or_b32_e32 v14, s50, v67
	v_or_b32_e32 v80, s50, v69
	v_or_b32_e32 v82, s50, v70
	v_ashrrev_i32_e32 v13, 31, v12
	v_ashrrev_i32_e32 v15, 31, v14
	v_ashrrev_i32_e32 v81, 31, v80
	v_ashrrev_i32_e32 v83, 31, v82
	v_or_b32_e32 v84, s50, v71
	v_or_b32_e32 v86, s50, v72
	v_lshlrev_b64 v[12:13], 12, v[12:13]
	v_lshlrev_b64 v[14:15], 12, v[14:15]
	v_lshlrev_b64 v[80:81], 12, v[80:81]
	v_lshlrev_b64 v[82:83], 12, v[82:83]
	v_ashrrev_i32_e32 v85, 31, v84
	v_ashrrev_i32_e32 v87, 31, v86
	v_lshl_add_u64 v[12:13], v[10:11], 0, v[12:13]
	v_lshl_add_u64 v[14:15], v[10:11], 0, v[14:15]
	v_lshl_add_u64 v[80:81], v[10:11], 0, v[80:81]
	v_lshl_add_u64 v[82:83], v[10:11], 0, v[82:83]
	v_lshlrev_b64 v[84:85], 12, v[84:85]
	v_lshlrev_b64 v[86:87], 12, v[86:87]
	v_lshl_add_u64 v[84:85], v[10:11], 0, v[84:85]
	v_lshl_add_u64 v[86:87], v[10:11], 0, v[86:87]
	global_load_dword v90, v[12:13], off nt
	global_load_dword v91, v[14:15], off nt
	s_nop 0
	global_load_dword v80, v[80:81], off nt
	s_nop 0
	global_load_dword v81, v[82:83], off nt
	s_nop 0
	global_load_dword v82, v[84:85], off nt
	global_load_dword v83, v[86:87], off nt
	v_or_b32_e32 v12, s50, v73
	v_or_b32_e32 v14, s50, v74
	v_ashrrev_i32_e32 v13, 31, v12
	v_ashrrev_i32_e32 v15, 31, v14
	v_lshlrev_b64 v[12:13], 12, v[12:13]
	v_lshlrev_b64 v[14:15], 12, v[14:15]
	v_lshl_add_u64 v[12:13], v[10:11], 0, v[12:13]
	v_lshl_add_u64 v[10:11], v[10:11], 0, v[14:15]
	global_load_dword v12, v[12:13], off nt
	s_nop 0
	global_load_dword v10, v[10:11], off nt
	s_waitcnt vmcnt(31)
	v_mul_f32_e32 v6, 0.5, v6
	v_add_u32_e32 v11, v5, v9
	s_waitcnt vmcnt(30)
	v_mul_f32_e32 v13, 0.5, v79
	ds_write2_b32 v11, v6, v13 offset1:66
	s_waitcnt vmcnt(29)
	v_mul_f32_e32 v6, 0.5, v92
	s_waitcnt vmcnt(28)
	v_mul_f32_e32 v13, 0.5, v93
	ds_write2_b32 v11, v6, v13 offset0:132 offset1:198
	s_waitcnt vmcnt(27)
	v_mul_f32_e32 v6, 0.5, v94
	s_waitcnt vmcnt(26)
	v_mul_f32_e32 v13, 0.5, v95
	v_add_u32_e32 v11, 0x400, v11
	ds_write2_b32 v11, v6, v13 offset0:8 offset1:74
	s_waitcnt vmcnt(25)
	v_mul_f32_e32 v6, 0.5, v96
	v_add_u32_e32 v11, v5, v24
	s_waitcnt vmcnt(24)
	v_mul_f32_e32 v13, 0.5, v97
	ds_write2_b32 v11, v6, v13 offset1:66
	s_waitcnt vmcnt(23)
	v_mul_f32_e32 v6, 0.5, v98
	s_waitcnt vmcnt(22)
	v_mul_f32_e32 v13, 0.5, v99
	ds_write2_b32 v11, v6, v13 offset0:132 offset1:198
	s_waitcnt vmcnt(21)
	v_mul_f32_e32 v6, 0.5, v100
	s_waitcnt vmcnt(20)
	v_mul_f32_e32 v13, 0.5, v101
	v_add_u32_e32 v11, 0x400, v11
	ds_write2_b32 v11, v6, v13 offset0:8 offset1:74
	s_waitcnt vmcnt(19)
	v_mul_f32_e32 v6, 0.5, v102
	v_add_u32_e32 v11, v5, v33
	s_waitcnt vmcnt(18)
	v_mul_f32_e32 v13, 0.5, v103
	ds_write2_b32 v11, v6, v13 offset1:66
	s_waitcnt vmcnt(17)
	v_mul_f32_e32 v6, 0.5, v104
	s_waitcnt vmcnt(16)
	v_mul_f32_e32 v13, 0.5, v105
	ds_write2_b32 v11, v6, v13 offset0:132 offset1:198
	v_add_u32_e32 v11, 0x400, v11
	s_ashr_i32 s51, s50, 31
	s_lshl_b64 s[50:51], s[50:51], 1
	s_add_u32 s50, s46, s50
	s_addc_u32 s51, s45, s51
	s_waitcnt vmcnt(15)
	v_mul_f32_e32 v6, 0.5, v106
	s_waitcnt vmcnt(14)
	v_mul_f32_e32 v13, 0.5, v107
	ds_write2_b32 v11, v6, v13 offset0:8 offset1:74
	s_waitcnt vmcnt(13)
	v_mul_f32_e32 v6, 0.5, v108
	v_add_u32_e32 v11, v5, v42
	s_waitcnt vmcnt(12)
	v_mul_f32_e32 v13, 0.5, v109
	ds_write2_b32 v11, v6, v13 offset1:66
	s_waitcnt vmcnt(11)
	v_mul_f32_e32 v6, 0.5, v110
	s_waitcnt vmcnt(10)
	v_mul_f32_e32 v13, 0.5, v111
	ds_write2_b32 v11, v6, v13 offset0:132 offset1:198
	s_waitcnt vmcnt(9)
	v_mul_f32_e32 v6, 0.5, v88
	s_waitcnt vmcnt(8)
	v_mul_f32_e32 v13, 0.5, v89
	v_add_u32_e32 v11, 0x400, v11
	ds_write2_b32 v11, v6, v13 offset0:8 offset1:74
	v_add_u32_e32 v11, v5, v48
	s_waitcnt vmcnt(7)
	v_mul_f32_e32 v6, 0.5, v90
	s_waitcnt vmcnt(6)
	v_mul_f32_e32 v13, 0.5, v91
	ds_write2_b32 v11, v6, v13 offset1:66
	s_waitcnt vmcnt(5)
	v_mul_f32_e32 v6, 0.5, v80
	s_waitcnt vmcnt(4)
	v_mul_f32_e32 v13, 0.5, v81
	ds_write2_b32 v11, v6, v13 offset0:132 offset1:198
	s_waitcnt vmcnt(3)
	v_mul_f32_e32 v6, 0.5, v82
	s_waitcnt vmcnt(2)
	v_mul_f32_e32 v13, 0.5, v83
	v_add_u32_e32 v11, 0x400, v11
	ds_write2_b32 v11, v6, v13 offset0:8 offset1:74
	s_waitcnt vmcnt(1)
	v_mul_f32_e32 v6, 0.5, v12
	s_waitcnt vmcnt(0)
	v_mul_f32_e32 v10, 0.5, v10
	ds_write2_b32 v11, v6, v10 offset0:140 offset1:206
	s_waitcnt lgkmcnt(0)
	ds_read2_b32 v[14:15], v47 offset0:33 offset1:41
	ds_read2_b32 v[80:81], v47 offset1:8
	ds_read2_b32 v[82:83], v47 offset0:66 offset1:74
	ds_read2_b32 v[84:85], v47 offset0:99 offset1:107
	ds_read2_b32 v[86:87], v47 offset0:132 offset1:140
	ds_read2_b32 v[88:89], v47 offset0:165 offset1:173
	ds_read2_b32 v[90:91], v47 offset0:198 offset1:206
	ds_read2_b32 v[92:93], v47 offset0:231 offset1:239
	v_lshlrev_b32_e32 v6, 1, v8
	v_lshl_add_u64 v[10:11], s[50:51], 0, v[6:7]
	v_or_b32_e32 v6, s2, v46
	v_mul_i32_i24_e32 v96, 0xb00, v6
	v_lshl_add_u64 v[94:95], v[10:11], 0, s[30:31]
	v_ashrrev_i32_e32 v97, 31, v96
	s_waitcnt lgkmcnt(6)
	v_cvt_pk_bf16_f32 v10, v80, v14
	s_waitcnt lgkmcnt(4)
	v_cvt_pk_bf16_f32 v11, v82, v84
	s_waitcnt lgkmcnt(2)
	v_cvt_pk_bf16_f32 v12, v86, v88
	s_waitcnt lgkmcnt(0)
	v_cvt_pk_bf16_f32 v13, v90, v92
	v_lshl_add_u64 v[96:97], v[96:97], 1, v[94:95]
	global_store_dwordx4 v[96:97], v[10:13], off
	v_or_b32_e32 v6, s2, v75
	v_mul_i32_i24_e32 v14, 0xb00, v6
	v_cvt_pk_bf16_f32 v10, v81, v15
	v_cvt_pk_bf16_f32 v11, v83, v85
	v_cvt_pk_bf16_f32 v12, v87, v89
	v_cvt_pk_bf16_f32 v13, v91, v93
	ds_read2_b32 v[80:81], v47 offset0:16 offset1:24
	ds_read2_b32 v[82:83], v47 offset0:49 offset1:57
	ds_read2_b32 v[84:85], v47 offset0:82 offset1:90
	ds_read2_b32 v[86:87], v47 offset0:115 offset1:123
	ds_read2_b32 v[88:89], v47 offset0:148 offset1:156
	ds_read2_b32 v[90:91], v47 offset0:181 offset1:189
	ds_read2_b32 v[92:93], v47 offset0:214 offset1:222
	ds_read2_b32 v[96:97], v47 offset0:247 offset1:255
	v_ashrrev_i32_e32 v15, 31, v14
	v_lshl_add_u64 v[14:15], v[14:15], 1, v[94:95]
	v_or_b32_e32 v6, s2, v76
	global_store_dwordx4 v[14:15], v[10:13], off
	v_mul_i32_i24_e32 v14, 0xb00, v6
	v_ashrrev_i32_e32 v15, 31, v14
	s_waitcnt lgkmcnt(6)
	v_cvt_pk_bf16_f32 v10, v80, v82
	s_waitcnt lgkmcnt(4)
	v_cvt_pk_bf16_f32 v11, v84, v86
	s_waitcnt lgkmcnt(2)
	v_cvt_pk_bf16_f32 v12, v88, v90
	s_waitcnt lgkmcnt(0)
	v_cvt_pk_bf16_f32 v13, v92, v96
	v_lshl_add_u64 v[14:15], v[14:15], 1, v[94:95]
	v_or_b32_e32 v6, s2, v77
	global_store_dwordx4 v[14:15], v[10:13], off
	v_mul_i32_i24_e32 v14, 0xb00, v6
	v_ashrrev_i32_e32 v15, 31, v14
	v_cvt_pk_bf16_f32 v10, v81, v83
	v_cvt_pk_bf16_f32 v11, v85, v87
	v_cvt_pk_bf16_f32 v12, v89, v91
	v_cvt_pk_bf16_f32 v13, v93, v97
	v_lshl_add_u64 v[14:15], v[14:15], 1, v[94:95]
	global_store_dwordx4 v[14:15], v[10:13], off
	s_waitcnt lgkmcnt(0)
	s_mov_b64 s[2:3], 0
; __device__ __forceinline__ void tr_item(const float* W, int ldw, int K, int k0, int srccol0, bf16* WT, int dstrow0, const float* gain, float scale, LAS float* scr, int lane, const float* gain2 = nullptr) {
;     ...
;     for (int i = 0; i < 32; ++i) { const int kk = 2 * i + (lane >> 5); float gsc = gain ? gain[k0 + kk] * scale : scale; if (gain2) gsc *= gain2[k0 + kk]; scr[kk * 33 + (lane & 31)] = W[(size_t)(k0 + kk) * ldw + srccol0 + (lane & 31)] * gsc; }
; __device__ __forceinline__ void phase_prep(const Args& a, unsigned char* ws, LAS unsigned char* lds, int vcu, int G, int tid, int wid, int lane) {
;     ...
;         if (r < I_OUT) { const int kb = r / 32, nb = r % 32; tr_item(a.in[15] + (size_t)l * DM * DM, DM, DM, kb * 64, nb * 32, (bf16*)(wl + WO_OUT), nb * 32, nullptr, 1.f, scr, lane); continue; }
.LBB0_19:
	s_andn2_b64 vcc, exec, s[2:3]
	s_cbranch_vccnz .LBB0_21
	s_lshl_b64 s[2:3], s[4:5], 22
	s_add_u32 s5, s22, s2
	s_mul_i32 s2, s4, 0xffffac00
	s_addc_u32 s3, s23, s3
	s_add_i32 s2, s38, s2
	s_and_b32 s2, s2, 0x3fc0
	s_add_i32 s20, s2, 0xffffd100
	s_and_b32 s2, s19, 0x3e0
	s_lshl_b32 s49, s2, 2
	s_add_u32 s50, s5, s49
	s_addc_u32 s51, s3, 0
	v_lshlrev_b32_e32 v6, 2, v4
	v_lshl_add_u64 v[10:11], s[50:51], 0, v[6:7]
	v_or_b32_e32 v6, s20, v2
	v_lshlrev_b64 v[12:13], 12, v[6:7]
	v_or_b32_e32 v6, s20, v16
	v_lshlrev_b64 v[14:15], 12, v[6:7]
	v_or_b32_e32 v6, s20, v17
	v_lshlrev_b64 v[80:81], 12, v[6:7]
	v_or_b32_e32 v6, s20, v19
	v_lshlrev_b64 v[82:83], 12, v[6:7]
	v_or_b32_e32 v6, s20, v20
	v_lshlrev_b64 v[84:85], 12, v[6:7]
	v_or_b32_e32 v6, s20, v22
	v_lshlrev_b64 v[86:87], 12, v[6:7]
	v_or_b32_e32 v6, s20, v23
	v_lshlrev_b64 v[88:89], 12, v[6:7]
	v_or_b32_e32 v6, s20, v25
	v_lshl_add_u64 v[12:13], v[10:11], 0, v[12:13]
	v_lshlrev_b64 v[90:91], 12, v[6:7]
	v_or_b32_e32 v6, s20, v26
	v_lshl_add_u64 v[14:15], v[10:11], 0, v[14:15]
	v_lshl_add_u64 v[80:81], v[10:11], 0, v[80:81]
	v_lshl_add_u64 v[82:83], v[10:11], 0, v[82:83]
	v_lshl_add_u64 v[84:85], v[10:11], 0, v[84:85]
	v_lshl_add_u64 v[86:87], v[10:11], 0, v[86:87]
	v_lshl_add_u64 v[88:89], v[10:11], 0, v[88:89]
	v_lshl_add_u64 v[90:91], v[10:11], 0, v[90:91]
	global_load_dword v79, v[12:13], off nt
	global_load_dword v92, v[14:15], off nt
	global_load_dword v93, v[80:81], off nt
	global_load_dword v94, v[82:83], off nt
	global_load_dword v95, v[84:85], off nt
	global_load_dword v96, v[86:87], off nt
	global_load_dword v97, v[88:89], off nt
	global_load_dword v98, v[90:91], off nt
	v_lshlrev_b64 v[12:13], 12, v[6:7]
	v_or_b32_e32 v6, s20, v28
	v_lshlrev_b64 v[14:15], 12, v[6:7]
	v_or_b32_e32 v6, s20, v29
	v_lshlrev_b64 v[80:81], 12, v[6:7]
	v_or_b32_e32 v6, s20, v31
	v_lshlrev_b64 v[82:83], 12, v[6:7]
	v_or_b32_e32 v6, s20, v32
	v_lshlrev_b64 v[84:85], 12, v[6:7]
	v_or_b32_e32 v6, s20, v34
	v_lshlrev_b64 v[86:87], 12, v[6:7]
	v_or_b32_e32 v6, s20, v35
	v_lshlrev_b64 v[88:89], 12, v[6:7]
	v_or_b32_e32 v6, s20, v37
	v_lshl_add_u64 v[12:13], v[10:11], 0, v[12:13]
	v_lshlrev_b64 v[90:91], 12, v[6:7]
	v_or_b32_e32 v6, s20, v38
	v_lshl_add_u64 v[14:15], v[10:11], 0, v[14:15]
	v_lshl_add_u64 v[80:81], v[10:11], 0, v[80:81]
	v_lshl_add_u64 v[82:83], v[10:11], 0, v[82:83]
	v_lshl_add_u64 v[84:85], v[10:11], 0, v[84:85]
	v_lshl_add_u64 v[86:87], v[10:11], 0, v[86:87]
	v_lshl_add_u64 v[88:89], v[10:11], 0, v[88:89]
	v_lshl_add_u64 v[90:91], v[10:11], 0, v[90:91]
	global_load_dword v99, v[12:13], off nt
	global_load_dword v100, v[14:15], off nt
	global_load_dword v101, v[80:81], off nt
	global_load_dword v102, v[82:83], off nt
	global_load_dword v103, v[84:85], off nt
	global_load_dword v104, v[86:87], off nt
	global_load_dword v105, v[88:89], off nt
	global_load_dword v106, v[90:91], off nt
	v_lshlrev_b64 v[12:13], 12, v[6:7]
	v_or_b32_e32 v6, s20, v40
	v_lshlrev_b64 v[14:15], 12, v[6:7]
	v_or_b32_e32 v6, s20, v41
	v_lshlrev_b64 v[80:81], 12, v[6:7]
	v_or_b32_e32 v6, s20, v43
	v_lshlrev_b64 v[82:83], 12, v[6:7]
	v_or_b32_e32 v6, s20, v61
	v_lshlrev_b64 v[84:85], 12, v[6:7]
	v_or_b32_e32 v6, s20, v62
	v_lshlrev_b64 v[86:87], 12, v[6:7]
	v_or_b32_e32 v6, s20, v63
	v_lshlrev_b64 v[88:89], 12, v[6:7]
	v_or_b32_e32 v6, s20, v64
	v_lshl_add_u64 v[12:13], v[10:11], 0, v[12:13]
	v_lshlrev_b64 v[90:91], 12, v[6:7]
	v_or_b32_e32 v6, s20, v65
	v_lshl_add_u64 v[14:15], v[10:11], 0, v[14:15]
	v_lshl_add_u64 v[80:81], v[10:11], 0, v[80:81]
	v_lshl_add_u64 v[82:83], v[10:11], 0, v[82:83]
	v_lshl_add_u64 v[84:85], v[10:11], 0, v[84:85]
	v_lshl_add_u64 v[86:87], v[10:11], 0, v[86:87]
	v_lshl_add_u64 v[88:89], v[10:11], 0, v[88:89]
	v_lshl_add_u64 v[90:91], v[10:11], 0, v[90:91]
	global_load_dword v107, v[12:13], off nt
	global_load_dword v108, v[14:15], off nt
	global_load_dword v109, v[80:81], off nt
	global_load_dword v110, v[82:83], off nt
	global_load_dword v111, v[84:85], off nt
	global_load_dword v112, v[86:87], off nt
	global_load_dword v113, v[88:89], off nt
	global_load_dword v114, v[90:91], off nt
	v_lshlrev_b64 v[12:13], 12, v[6:7]
	v_or_b32_e32 v6, s20, v67
	v_lshlrev_b64 v[14:15], 12, v[6:7]
	v_or_b32_e32 v6, s20, v69
	v_lshlrev_b64 v[80:81], 12, v[6:7]
	v_or_b32_e32 v6, s20, v70
	v_lshlrev_b64 v[82:83], 12, v[6:7]
	v_or_b32_e32 v6, s20, v71
	v_lshlrev_b64 v[84:85], 12, v[6:7]
	v_or_b32_e32 v6, s20, v72
	v_lshlrev_b64 v[86:87], 12, v[6:7]
	v_or_b32_e32 v6, s20, v73
	v_lshlrev_b64 v[88:89], 12, v[6:7]
	v_or_b32_e32 v6, s20, v74
	v_lshlrev_b64 v[90:91], 12, v[6:7]
	v_lshl_add_u64 v[12:13], v[10:11], 0, v[12:13]
	v_lshl_add_u64 v[14:15], v[10:11], 0, v[14:15]
	v_lshl_add_u64 v[80:81], v[10:11], 0, v[80:81]
	v_lshl_add_u64 v[82:83], v[10:11], 0, v[82:83]
	v_lshl_add_u64 v[84:85], v[10:11], 0, v[84:85]
	v_lshl_add_u64 v[86:87], v[10:11], 0, v[86:87]
	v_lshl_add_u64 v[88:89], v[10:11], 0, v[88:89]
	v_lshl_add_u64 v[10:11], v[10:11], 0, v[90:91]
	global_load_dword v6, v[12:13], off nt
	s_nop 0
	global_load_dword v12, v[14:15], off nt
	global_load_dword v13, v[80:81], off nt
	s_nop 0
	global_load_dword v14, v[82:83], off nt
	global_load_dword v15, v[84:85], off nt
	global_load_dword v80, v[86:87], off nt
	global_load_dword v81, v[88:89], off nt
	s_nop 0
	global_load_dword v10, v[10:11], off nt
	v_add_u32_e32 v11, v5, v9
	s_waitcnt vmcnt(30)
; #define LAS __attribute__((address_space(3)))
; #define LDS_WAIT() asm volatile("s_waitcnt lgkmcnt(0)" ::: "memory")
; __device__ __forceinline__ unsigned pkbf(float lo, float hi) { typedef __bf16 bf2_t __attribute__((ext_vector_type(2))); f32x2 v = {lo, hi}; bf2_t b = __builtin_convertvector(v, bf2_t); return __builtin_bit_cast(unsigned, b); }
; __device__ __forceinline__ void tr_item(const float* W, int ldw, int K, int k0, int srccol0, bf16* WT, int dstrow0, const float* gain, float scale, LAS float* scr, int lane, const float* gain2 = nullptr) {
;     ...
;     for (int i = 0; i < 32; ++i) { const int kk = 2 * i + (lane >> 5); float gsc = gain ? gain[k0 + kk] * scale : scale; if (gain2) gsc *= gain2[k0 + kk]; scr[kk * 33 + (lane & 31)] = W[(size_t)(k0 + kk) * ldw + srccol0 + (lane & 31)] * gsc; }
;     LDS_WAIT();
;     const int c = lane & 7;
; #pragma unroll
;     for (int j = 0; j < 4; ++j) { const int n = (lane >> 3) + 8 * j; const LAS float* s = scr + (8 * c) * 33 + n;
;         u32x4 o; o.x = pkbf(s[0 * 33], s[1 * 33]); o.y = pkbf(s[2 * 33], s[3 * 33]); o.z = pkbf(s[4 * 33], s[5 * 33]); o.w = pkbf(s[6 * 33], s[7 * 33]);
;         *(u32x4*)(WT + (size_t)(dstrow0 + n) * K + k0 + 8 * c) = o; }
;     LDS_WAIT();
; __device__ __forceinline__ void phase_prep(const Args& a, unsigned char* ws, LAS unsigned char* lds, int vcu, int G, int tid, int wid, int lane) {
;     ...
;         if (r < I_OUT) { const int kb = r / 32, nb = r % 32; tr_item(a.in[15] + (size_t)l * DM * DM, DM, DM, kb * 64, nb * 32, (bf16*)(wl + WO_OUT), nb * 32, nullptr, 1.f, scr, lane); continue; }
	ds_write2_b32 v11, v79, v92 offset1:66
	s_waitcnt vmcnt(28)
	ds_write2_b32 v11, v93, v94 offset0:132 offset1:198
	v_add_u32_e32 v11, 0x400, v11
	s_waitcnt vmcnt(26)
	ds_write2_b32 v11, v95, v96 offset0:8 offset1:74
	v_add_u32_e32 v11, v5, v24
	s_waitcnt vmcnt(24)
	ds_write2_b32 v11, v97, v98 offset1:66
	s_waitcnt vmcnt(22)
	ds_write2_b32 v11, v99, v100 offset0:132 offset1:198
	v_add_u32_e32 v11, 0x400, v11
	s_waitcnt vmcnt(20)
	ds_write2_b32 v11, v101, v102 offset0:8 offset1:74
	v_add_u32_e32 v11, v5, v33
	s_waitcnt vmcnt(18)
	ds_write2_b32 v11, v103, v104 offset1:66
	s_waitcnt vmcnt(16)
	ds_write2_b32 v11, v105, v106 offset0:132 offset1:198
	v_add_u32_e32 v11, 0x400, v11
	s_lshl_b64 s[50:51], s[20:21], 1
	s_add_u32 s50, s46, s50
	s_addc_u32 s51, s45, s51
	s_waitcnt vmcnt(14)
	ds_write2_b32 v11, v107, v108 offset0:8 offset1:74
	v_add_u32_e32 v11, v5, v42
	s_waitcnt vmcnt(12)
	ds_write2_b32 v11, v109, v110 offset1:66
	s_waitcnt vmcnt(10)
	ds_write2_b32 v11, v111, v112 offset0:132 offset1:198
	v_add_u32_e32 v11, 0x400, v11
	s_waitcnt vmcnt(8)
	ds_write2_b32 v11, v113, v114 offset0:8 offset1:74
	v_add_u32_e32 v11, v5, v48
	s_waitcnt vmcnt(6)
	ds_write2_b32 v11, v6, v12 offset1:66
	s_waitcnt vmcnt(4)
	ds_write2_b32 v11, v13, v14 offset0:132 offset1:198
	v_add_u32_e32 v6, 0x400, v11
	s_waitcnt vmcnt(2)
	ds_write2_b32 v6, v15, v80 offset0:8 offset1:74
	s_waitcnt vmcnt(0)
	ds_write2_b32 v6, v81, v10 offset0:140 offset1:206
	s_waitcnt lgkmcnt(0)
	ds_read2_b32 v[14:15], v47 offset0:33 offset1:41
	ds_read2_b32 v[80:81], v47 offset1:8
	ds_read2_b32 v[82:83], v47 offset0:66 offset1:74
	ds_read2_b32 v[84:85], v47 offset0:99 offset1:107
	ds_read2_b32 v[86:87], v47 offset0:132 offset1:140
	ds_read2_b32 v[88:89], v47 offset0:165 offset1:173
	ds_read2_b32 v[90:91], v47 offset0:198 offset1:206
	ds_read2_b32 v[92:93], v47 offset0:231 offset1:239
	v_lshlrev_b32_e32 v6, 1, v8
	v_lshl_add_u64 v[10:11], s[50:51], 0, v[6:7]
	v_or_b32_e32 v6, s2, v46
	v_lshl_add_u64 v[94:95], v[10:11], 0, s[34:35]
	v_lshlrev_b32_e32 v6, 11, v6
	s_waitcnt lgkmcnt(6)
	v_cvt_pk_bf16_f32 v10, v80, v14
	s_waitcnt lgkmcnt(4)
	v_cvt_pk_bf16_f32 v11, v82, v84
	s_waitcnt lgkmcnt(2)
	v_cvt_pk_bf16_f32 v12, v86, v88
	s_waitcnt lgkmcnt(0)
	v_cvt_pk_bf16_f32 v13, v90, v92
	v_lshl_add_u64 v[96:97], v[94:95], 0, v[6:7]
	global_store_dwordx4 v[96:97], v[10:13], off
	v_or_b32_e32 v6, s2, v75
	v_lshlrev_b32_e32 v6, 11, v6
	v_cvt_pk_bf16_f32 v10, v81, v15
	v_cvt_pk_bf16_f32 v11, v83, v85
	v_cvt_pk_bf16_f32 v12, v87, v89
	v_cvt_pk_bf16_f32 v13, v91, v93
	ds_read2_b32 v[80:81], v47 offset0:49 offset1:57
	ds_read2_b32 v[82:83], v47 offset0:16 offset1:24
	ds_read2_b32 v[84:85], v47 offset0:82 offset1:90
	ds_read2_b32 v[86:87], v47 offset0:115 offset1:123
	ds_read2_b32 v[88:89], v47 offset0:148 offset1:156
	ds_read2_b32 v[90:91], v47 offset0:181 offset1:189
	ds_read2_b32 v[92:93], v47 offset0:214 offset1:222
	ds_read2_b32 v[96:97], v47 offset0:247 offset1:255
	v_lshl_add_u64 v[14:15], v[94:95], 0, v[6:7]
	v_or_b32_e32 v6, s2, v76
	v_lshlrev_b32_e32 v6, 11, v6
	global_store_dwordx4 v[14:15], v[10:13], off
	v_lshl_add_u64 v[14:15], v[94:95], 0, v[6:7]
	v_or_b32_e32 v6, s2, v77
	s_waitcnt lgkmcnt(6)
	v_cvt_pk_bf16_f32 v10, v82, v80
	s_waitcnt lgkmcnt(4)
	v_cvt_pk_bf16_f32 v11, v84, v86
	s_waitcnt lgkmcnt(2)
	v_cvt_pk_bf16_f32 v12, v88, v90
	s_waitcnt lgkmcnt(0)
	v_cvt_pk_bf16_f32 v13, v92, v96
	v_lshlrev_b32_e32 v6, 11, v6
	global_store_dwordx4 v[14:15], v[10:13], off
	v_lshl_add_u64 v[14:15], v[94:95], 0, v[6:7]
	s_nop 0
	v_cvt_pk_bf16_f32 v10, v83, v81
	v_cvt_pk_bf16_f32 v11, v85, v87
	v_cvt_pk_bf16_f32 v12, v89, v91
	v_cvt_pk_bf16_f32 v13, v93, v97
	global_store_dwordx4 v[14:15], v[10:13], off
	s_waitcnt lgkmcnt(0)

; __device__ __forceinline__ void tr_item(const float* W, int ldw, int K, int k0, int srccol0, bf16* WT, int dstrow0, const float* gain, float scale, LAS float* scr, int lane, const float* gain2 = nullptr) {
;     ...
;     for (int i = 0; i < 32; ++i) { const int kk = 2 * i + (lane >> 5); float gsc = gain ? gain[k0 + kk] * scale : scale; if (gain2) gsc *= gain2[k0 + kk]; scr[kk * 33 + (lane & 31)] = W[(size_t)(k0 + kk) * ldw + srccol0 + (lane & 31)] * gsc; }
; __device__ __forceinline__ void phase_prep(const Args& a, unsigned char* ws, LAS unsigned char* lds, int vcu, int G, int tid, int wid, int lane) {
;     ...
;             tr_item(a.in[7] + (size_t)l * DM * NIN, NIN, DM, kb * 64, src, (bf16*)(wl + WO_IN), n0, a.in[6] + l * DM, type == 1 ? 0.08838834764831845f : 1.f, scr, lane);
.LBB0_27:
	s_mul_i32 s3, s4, 0xe00000
	s_mul_hi_i32 s2, s4, 0xe00000
	s_add_u32 s53, s24, s3
	s_addc_u32 s54, s25, s2
	s_lshl_b32 s2, s49, 6
	s_and_b32 s49, s2, 0xffc0
	s_lshl_b32 s2, s4, 10
	s_ashr_i32 s3, s2, 31
	s_lshl_b64 s[2:3], s[2:3], 2
	s_add_u32 s50, s10, s2
	s_addc_u32 s51, s11, s3
	s_and_b32 s2, s52, 0x70
	s_cmp_eq_u32 s2, 16
	s_cselect_b64 vcc, -1, 0
	s_lshl_b64 s[2:3], s[20:21], 2
	s_add_u32 s2, s53, s2
	s_addc_u32 s3, s54, s3
	s_mul_i32 s20, s49, 0x3800
	s_add_u32 s56, s2, s20
	s_addc_u32 s57, s3, 0
	s_lshl_b32 s20, s49, 2
	s_add_u32 s58, s50, s20
	s_addc_u32 s59, s51, 0
	s_lshl_b32 s2, s49, 1
	s_lshl_b32 s3, s5, 11
	s_add_i32 s2, s2, s3
	s_add_u32 s2, s46, s2
	s_addc_u32 s3, s45, 0
	s_add_u32 s2, s2, s36
	s_addc_u32 s3, s3, s37
	v_mul_u32_u24_e32 v118, 0x3800, v2
	v_lshlrev_b32_e32 v119, 2, v8
	v_lshl_add_u32 v118, v4, 2, v118
	s_nop 0
	global_load_dwordx4 v[152:155], v119, s[58:59]
	global_load_dwordx4 v[156:159], v119, s[58:59] offset:16
	global_load_dword v120, v118, s[56:57] nt
	s_add_u32 s56, s56, 0x7000
	s_addc_u32 s57, s57, 0
	global_load_dword v121, v118, s[56:57] nt
	s_add_u32 s56, s56, 0x7000
	s_addc_u32 s57, s57, 0
	global_load_dword v122, v118, s[56:57] nt
	s_add_u32 s56, s56, 0x7000
	s_addc_u32 s57, s57, 0
	global_load_dword v123, v118, s[56:57] nt
	s_add_u32 s56, s56, 0x7000
	s_addc_u32 s57, s57, 0
	global_load_dword v124, v118, s[56:57] nt
	s_add_u32 s56, s56, 0x7000
	s_addc_u32 s57, s57, 0
	global_load_dword v125, v118, s[56:57] nt
	s_add_u32 s56, s56, 0x7000
	s_addc_u32 s57, s57, 0
	global_load_dword v126, v118, s[56:57] nt
	s_add_u32 s56, s56, 0x7000
	s_addc_u32 s57, s57, 0
	global_load_dword v127, v118, s[56:57] nt
	s_add_u32 s56, s56, 0x7000
	s_addc_u32 s57, s57, 0
	global_load_dword v128, v118, s[56:57] nt
	s_add_u32 s56, s56, 0x7000
	s_addc_u32 s57, s57, 0
	global_load_dword v129, v118, s[56:57] nt
	s_add_u32 s56, s56, 0x7000
	s_addc_u32 s57, s57, 0
	global_load_dword v130, v118, s[56:57] nt
	s_add_u32 s56, s56, 0x7000
	s_addc_u32 s57, s57, 0
	global_load_dword v131, v118, s[56:57] nt
	s_add_u32 s56, s56, 0x7000
	s_addc_u32 s57, s57, 0
	global_load_dword v132, v118, s[56:57] nt
	s_add_u32 s56, s56, 0x7000
	s_addc_u32 s57, s57, 0
	global_load_dword v133, v118, s[56:57] nt
	s_add_u32 s56, s56, 0x7000
	s_addc_u32 s57, s57, 0
	global_load_dword v134, v118, s[56:57] nt
	s_add_u32 s56, s56, 0x7000
	s_addc_u32 s57, s57, 0
	global_load_dword v135, v118, s[56:57] nt
	s_add_u32 s56, s56, 0x7000
	s_addc_u32 s57, s57, 0
	global_load_dword v136, v118, s[56:57] nt
	s_add_u32 s56, s56, 0x7000
	s_addc_u32 s57, s57, 0
	global_load_dword v137, v118, s[56:57] nt
	s_add_u32 s56, s56, 0x7000
	s_addc_u32 s57, s57, 0
	global_load_dword v138, v118, s[56:57] nt
	s_add_u32 s56, s56, 0x7000
	s_addc_u32 s57, s57, 0
	global_load_dword v139, v118, s[56:57] nt
	s_add_u32 s56, s56, 0x7000
	s_addc_u32 s57, s57, 0
	global_load_dword v140, v118, s[56:57] nt
	s_add_u32 s56, s56, 0x7000
	s_addc_u32 s57, s57, 0
	global_load_dword v141, v118, s[56:57] nt
	s_add_u32 s56, s56, 0x7000
	s_addc_u32 s57, s57, 0
	global_load_dword v142, v118, s[56:57] nt
	s_add_u32 s56, s56, 0x7000
	s_addc_u32 s57, s57, 0
	global_load_dword v143, v118, s[56:57] nt
	s_add_u32 s56, s56, 0x7000
	s_addc_u32 s57, s57, 0
	global_load_dword v144, v118, s[56:57] nt
	s_add_u32 s56, s56, 0x7000
	s_addc_u32 s57, s57, 0
	global_load_dword v145, v118, s[56:57] nt
	s_add_u32 s56, s56, 0x7000
	s_addc_u32 s57, s57, 0
	global_load_dword v146, v118, s[56:57] nt
	s_add_u32 s56, s56, 0x7000
	s_addc_u32 s57, s57, 0
	global_load_dword v147, v118, s[56:57] nt
	s_add_u32 s56, s56, 0x7000
	s_addc_u32 s57, s57, 0
	global_load_dword v148, v118, s[56:57] nt
	s_add_u32 s56, s56, 0x7000
	s_addc_u32 s57, s57, 0
	global_load_dword v149, v118, s[56:57] nt
	s_add_u32 s56, s56, 0x7000
	s_addc_u32 s57, s57, 0
	global_load_dword v150, v118, s[56:57] nt
	s_add_u32 s56, s56, 0x7000
	s_addc_u32 s57, s57, 0
	global_load_dword v151, v118, s[56:57] nt
	v_cndmask_b32_e32 v184, 1.0, v78, vcc
	v_add_u32_e32 v119, v5, v9
	s_waitcnt vmcnt(28)
	ds_write_b32 v119, v120
	ds_write_b32 v119, v121 offset:264
	ds_write_b32 v119, v122 offset:528
	ds_write_b32 v119, v123 offset:792
	s_waitcnt vmcnt(24)
	ds_write_b32 v119, v124 offset:1056
	ds_write_b32 v119, v125 offset:1320
	ds_write_b32 v119, v126 offset:1584
	ds_write_b32 v119, v127 offset:1848
	s_waitcnt vmcnt(20)
	ds_write_b32 v119, v128 offset:2112
	ds_write_b32 v119, v129 offset:2376
	ds_write_b32 v119, v130 offset:2640
	ds_write_b32 v119, v131 offset:2904
	s_waitcnt vmcnt(16)
; #define LAS __attribute__((address_space(3)))
; #define LDS_WAIT() asm volatile("s_waitcnt lgkmcnt(0)" ::: "memory")
; __device__ __forceinline__ unsigned pkbf(float lo, float hi) { typedef __bf16 bf2_t __attribute__((ext_vector_type(2))); f32x2 v = {lo, hi}; bf2_t b = __builtin_convertvector(v, bf2_t); return __builtin_bit_cast(unsigned, b); }
; __device__ __forceinline__ void tr_item(const float* W, int ldw, int K, int k0, int srccol0, bf16* WT, int dstrow0, const float* gain, float scale, LAS float* scr, int lane, const float* gain2 = nullptr) {
;     ...
;     for (int i = 0; i < 32; ++i) { const int kk = 2 * i + (lane >> 5); float gsc = gain ? gain[k0 + kk] * scale : scale; if (gain2) gsc *= gain2[k0 + kk]; scr[kk * 33 + (lane & 31)] = W[(size_t)(k0 + kk) * ldw + srccol0 + (lane & 31)] * gsc; }
;     LDS_WAIT();
;     const int c = lane & 7;
; #pragma unroll
;     for (int j = 0; j < 4; ++j) { const int n = (lane >> 3) + 8 * j; const LAS float* s = scr + (8 * c) * 33 + n;
;         u32x4 o; o.x = pkbf(s[0 * 33], s[1 * 33]); o.y = pkbf(s[2 * 33], s[3 * 33]); o.z = pkbf(s[4 * 33], s[5 * 33]); o.w = pkbf(s[6 * 33], s[7 * 33]);
;         *(u32x4*)(WT + (size_t)(dstrow0 + n) * K + k0 + 8 * c) = o; }
;     LDS_WAIT();
	ds_write_b32 v119, v132 offset:3168
	ds_write_b32 v119, v133 offset:3432
	ds_write_b32 v119, v134 offset:3696
	ds_write_b32 v119, v135 offset:3960
	s_waitcnt vmcnt(12)
	ds_write_b32 v119, v136 offset:4224
	ds_write_b32 v119, v137 offset:4488
	ds_write_b32 v119, v138 offset:4752
	ds_write_b32 v119, v139 offset:5016
	s_waitcnt vmcnt(8)
	ds_write_b32 v119, v140 offset:5280
	ds_write_b32 v119, v141 offset:5544
	ds_write_b32 v119, v142 offset:5808
	ds_write_b32 v119, v143 offset:6072
	s_waitcnt vmcnt(4)
	ds_write_b32 v119, v144 offset:6336
	ds_write_b32 v119, v145 offset:6600
	ds_write_b32 v119, v146 offset:6864
	ds_write_b32 v119, v147 offset:7128
	s_waitcnt vmcnt(0)
	ds_write_b32 v119, v148 offset:7392
	ds_write_b32 v119, v149 offset:7656
	ds_write_b32 v119, v150 offset:7920
	ds_write_b32 v119, v151 offset:8184
	v_mul_f32_e32 v152, v184, v152
	v_mul_f32_e32 v153, v184, v153
	v_mul_f32_e32 v154, v184, v154
	v_mul_f32_e32 v155, v184, v155
	v_mul_f32_e32 v156, v184, v156
	v_mul_f32_e32 v157, v184, v157
	v_mul_f32_e32 v158, v184, v158
	v_mul_f32_e32 v159, v184, v159
	s_waitcnt lgkmcnt(0)
	ds_read2_b32 v[120:121], v47 offset1:8
	ds_read2_b32 v[122:123], v47 offset0:33 offset1:41
	ds_read2_b32 v[124:125], v47 offset0:66 offset1:74
	ds_read2_b32 v[126:127], v47 offset0:99 offset1:107
	ds_read2_b32 v[128:129], v47 offset0:132 offset1:140
	ds_read2_b32 v[130:131], v47 offset0:165 offset1:173
	ds_read2_b32 v[132:133], v47 offset0:198 offset1:206
	ds_read2_b32 v[134:135], v47 offset0:231 offset1:239
	ds_read2_b32 v[136:137], v47 offset0:16 offset1:24
	ds_read2_b32 v[138:139], v47 offset0:49 offset1:57
	ds_read2_b32 v[140:141], v47 offset0:82 offset1:90
	ds_read2_b32 v[142:143], v47 offset0:115 offset1:123
	ds_read2_b32 v[144:145], v47 offset0:148 offset1:156
	ds_read2_b32 v[146:147], v47 offset0:181 offset1:189
	ds_read2_b32 v[148:149], v47 offset0:214 offset1:222
	ds_read2_b32 v[150:151], v47 offset0:247 offset1:255
	v_lshlrev_b32_e32 v118, 11, v46
	v_lshl_add_u32 v118, v8, 1, v118
	v_add_u32_e32 v186, 0x4000, v118
	v_add_u32_e32 v187, 0x8000, v118
	v_add_u32_e32 v188, 0xc000, v118
	s_waitcnt lgkmcnt(15)
	v_pk_mul_f32 v[120:121], v[120:121], v[152:153] op_sel_hi:[1,0]
	s_waitcnt lgkmcnt(14)
	v_pk_mul_f32 v[122:123], v[122:123], v[152:153] op_sel:[0,1] op_sel_hi:[1,1]
	s_waitcnt lgkmcnt(13)
	v_pk_mul_f32 v[124:125], v[124:125], v[154:155] op_sel_hi:[1,0]
	s_waitcnt lgkmcnt(12)
	v_pk_mul_f32 v[126:127], v[126:127], v[154:155] op_sel:[0,1] op_sel_hi:[1,1]
	s_waitcnt lgkmcnt(11)
	v_pk_mul_f32 v[128:129], v[128:129], v[156:157] op_sel_hi:[1,0]
	s_waitcnt lgkmcnt(10)
	v_pk_mul_f32 v[130:131], v[130:131], v[156:157] op_sel:[0,1] op_sel_hi:[1,1]
	s_waitcnt lgkmcnt(9)
	v_pk_mul_f32 v[132:133], v[132:133], v[158:159] op_sel_hi:[1,0]
	s_waitcnt lgkmcnt(8)
	v_pk_mul_f32 v[134:135], v[134:135], v[158:159] op_sel:[0,1] op_sel_hi:[1,1]
	v_cvt_pk_bf16_f32 v168, v120, v122
	v_cvt_pk_bf16_f32 v169, v124, v126
	v_cvt_pk_bf16_f32 v170, v128, v130
	v_cvt_pk_bf16_f32 v171, v132, v134
	global_store_dwordx4 v118, v[168:171], s[2:3]
	v_cvt_pk_bf16_f32 v172, v121, v123
	v_cvt_pk_bf16_f32 v173, v125, v127
	v_cvt_pk_bf16_f32 v174, v129, v131
	v_cvt_pk_bf16_f32 v175, v133, v135
	global_store_dwordx4 v186, v[172:175], s[2:3]
	s_waitcnt lgkmcnt(7)
	v_pk_mul_f32 v[136:137], v[136:137], v[152:153] op_sel_hi:[1,0]
	s_waitcnt lgkmcnt(6)
	v_pk_mul_f32 v[138:139], v[138:139], v[152:153] op_sel:[0,1] op_sel_hi:[1,1]
	s_waitcnt lgkmcnt(5)
	v_pk_mul_f32 v[140:141], v[140:141], v[154:155] op_sel_hi:[1,0]
	s_waitcnt lgkmcnt(4)
	v_pk_mul_f32 v[142:143], v[142:143], v[154:155] op_sel:[0,1] op_sel_hi:[1,1]
	s_waitcnt lgkmcnt(3)
	v_pk_mul_f32 v[144:145], v[144:145], v[156:157] op_sel_hi:[1,0]
	s_waitcnt lgkmcnt(2)
	v_pk_mul_f32 v[146:147], v[146:147], v[156:157] op_sel:[0,1] op_sel_hi:[1,1]
	s_waitcnt lgkmcnt(1)
	v_pk_mul_f32 v[148:149], v[148:149], v[158:159] op_sel_hi:[1,0]
	s_waitcnt lgkmcnt(0)
	v_pk_mul_f32 v[150:151], v[150:151], v[158:159] op_sel:[0,1] op_sel_hi:[1,1]
	v_cvt_pk_bf16_f32 v176, v136, v138
	v_cvt_pk_bf16_f32 v177, v140, v142
	v_cvt_pk_bf16_f32 v178, v144, v146
	v_cvt_pk_bf16_f32 v179, v148, v150
	global_store_dwordx4 v187, v[176:179], s[2:3]
	v_cvt_pk_bf16_f32 v180, v137, v139
	v_cvt_pk_bf16_f32 v181, v141, v143
	v_cvt_pk_bf16_f32 v182, v145, v147
	v_cvt_pk_bf16_f32 v183, v149, v151
	global_store_dwordx4 v188, v[180:183], s[2:3]

; __device__ __forceinline__ void tr_item(const float* W, int ldw, int K, int k0, int srccol0, bf16* WT, int dstrow0, const float* gain, float scale, LAS float* scr, int lane, const float* gain2 = nullptr) {
;     ...
;     for (int i = 0; i < 32; ++i) { const int kk = 2 * i + (lane >> 5); float gsc = gain ? gain[k0 + kk] * scale : scale; if (gain2) gsc *= gain2[k0 + kk]; scr[kk * 33 + (lane & 31)] = W[(size_t)(k0 + kk) * ldw + srccol0 + (lane & 31)] * gsc; }
; __device__ __forceinline__ void phase_prep(const Args& a, unsigned char* ws, LAS unsigned char* lds, int vcu, int G, int tid, int wid, int lane) {
;     ...
;         if (r < I_D) { const int kb = r / 32, nb = r % 32; tr_item(a.in[5] + (size_t)l * FF * DM, DM, FF, kb * 64, nb * 32, (bf16*)(wl + WO_D1), nb * 32, nullptr, 0.5f, scr, lane); continue; }
.LBB0_77:
	s_andn2_b64 vcc, exec, s[2:3]
	s_cbranch_vccnz .LBB0_79
	s_mul_i32 s3, s4, 0xb00000
	s_mul_hi_i32 s2, s4, 0xb00000
	s_add_u32 s3, s8, s3
	s_addc_u32 s5, s9, s2
	s_mul_i32 s2, s4, 0xffffac00
	s_add_i32 s2, s38, s2
	s_and_b32 s2, s2, 0x3fc0
	s_add_i32 s20, s2, 0xffffea00
	s_and_b32 s2, s19, 0x3e0
	s_lshl_b32 s49, s2, 2
	s_add_u32 s50, s3, s49
	s_addc_u32 s51, s5, 0
	v_lshlrev_b32_e32 v6, 2, v4
	v_lshl_add_u64 v[10:11], s[50:51], 0, v[6:7]
	v_or_b32_e32 v6, s20, v2
	v_lshlrev_b64 v[12:13], 12, v[6:7]
	v_or_b32_e32 v6, s20, v16
	v_lshlrev_b64 v[14:15], 12, v[6:7]
	v_or_b32_e32 v6, s20, v17
	v_lshlrev_b64 v[80:81], 12, v[6:7]
	v_or_b32_e32 v6, s20, v19
	v_lshlrev_b64 v[82:83], 12, v[6:7]
	v_or_b32_e32 v6, s20, v20
	v_lshlrev_b64 v[84:85], 12, v[6:7]
	v_or_b32_e32 v6, s20, v22
	v_lshlrev_b64 v[86:87], 12, v[6:7]
	v_or_b32_e32 v6, s20, v23
	v_lshlrev_b64 v[88:89], 12, v[6:7]
	v_or_b32_e32 v6, s20, v25
	v_lshl_add_u64 v[12:13], v[10:11], 0, v[12:13]
	v_lshlrev_b64 v[90:91], 12, v[6:7]
	v_or_b32_e32 v6, s20, v26
	v_lshl_add_u64 v[14:15], v[10:11], 0, v[14:15]
	v_lshl_add_u64 v[80:81], v[10:11], 0, v[80:81]
	v_lshl_add_u64 v[82:83], v[10:11], 0, v[82:83]
	v_lshl_add_u64 v[84:85], v[10:11], 0, v[84:85]
	v_lshl_add_u64 v[86:87], v[10:11], 0, v[86:87]
	v_lshl_add_u64 v[88:89], v[10:11], 0, v[88:89]
	v_lshl_add_u64 v[90:91], v[10:11], 0, v[90:91]
	global_load_dword v79, v[12:13], off nt
	global_load_dword v92, v[14:15], off nt
	global_load_dword v93, v[80:81], off nt
	global_load_dword v94, v[82:83], off nt
	global_load_dword v95, v[84:85], off nt
	global_load_dword v96, v[86:87], off nt
	global_load_dword v97, v[88:89], off nt
	global_load_dword v98, v[90:91], off nt
	v_lshlrev_b64 v[12:13], 12, v[6:7]
	v_or_b32_e32 v6, s20, v28
	v_lshlrev_b64 v[14:15], 12, v[6:7]
	v_or_b32_e32 v6, s20, v29
	v_lshlrev_b64 v[80:81], 12, v[6:7]
	v_or_b32_e32 v6, s20, v31
	v_lshlrev_b64 v[82:83], 12, v[6:7]
	v_or_b32_e32 v6, s20, v32
	v_lshlrev_b64 v[84:85], 12, v[6:7]
	v_or_b32_e32 v6, s20, v34
	v_lshlrev_b64 v[86:87], 12, v[6:7]
	v_or_b32_e32 v6, s20, v35
	v_lshlrev_b64 v[88:89], 12, v[6:7]
	v_or_b32_e32 v6, s20, v37
	v_lshl_add_u64 v[12:13], v[10:11], 0, v[12:13]
	v_lshlrev_b64 v[90:91], 12, v[6:7]
	v_or_b32_e32 v6, s20, v38
	v_lshl_add_u64 v[14:15], v[10:11], 0, v[14:15]
	v_lshl_add_u64 v[80:81], v[10:11], 0, v[80:81]
	v_lshl_add_u64 v[82:83], v[10:11], 0, v[82:83]
	v_lshl_add_u64 v[84:85], v[10:11], 0, v[84:85]
	v_lshl_add_u64 v[86:87], v[10:11], 0, v[86:87]
	v_lshl_add_u64 v[88:89], v[10:11], 0, v[88:89]
	v_lshl_add_u64 v[90:91], v[10:11], 0, v[90:91]
	global_load_dword v99, v[12:13], off nt
	global_load_dword v100, v[14:15], off nt
	global_load_dword v101, v[80:81], off nt
	global_load_dword v102, v[82:83], off nt
	global_load_dword v103, v[84:85], off nt
	global_load_dword v104, v[86:87], off nt
	global_load_dword v105, v[88:89], off nt
	global_load_dword v106, v[90:91], off nt
	v_lshlrev_b64 v[12:13], 12, v[6:7]
	v_or_b32_e32 v6, s20, v40
	v_lshlrev_b64 v[14:15], 12, v[6:7]
	v_or_b32_e32 v6, s20, v41
	v_lshlrev_b64 v[80:81], 12, v[6:7]
	v_or_b32_e32 v6, s20, v43
	v_lshlrev_b64 v[82:83], 12, v[6:7]
	v_or_b32_e32 v6, s20, v61
	v_lshlrev_b64 v[84:85], 12, v[6:7]
	v_or_b32_e32 v6, s20, v62
	v_lshlrev_b64 v[86:87], 12, v[6:7]
	v_or_b32_e32 v6, s20, v63
	v_lshlrev_b64 v[88:89], 12, v[6:7]
	v_or_b32_e32 v6, s20, v64
	v_lshl_add_u64 v[12:13], v[10:11], 0, v[12:13]
	v_lshl_add_u64 v[88:89], v[10:11], 0, v[88:89]
	v_lshlrev_b64 v[90:91], 12, v[6:7]
	v_or_b32_e32 v6, s20, v65
	v_lshl_add_u64 v[14:15], v[10:11], 0, v[14:15]
	v_lshl_add_u64 v[80:81], v[10:11], 0, v[80:81]
	v_lshl_add_u64 v[82:83], v[10:11], 0, v[82:83]
	v_lshl_add_u64 v[84:85], v[10:11], 0, v[84:85]
	v_lshl_add_u64 v[86:87], v[10:11], 0, v[86:87]
	v_lshl_add_u64 v[90:91], v[10:11], 0, v[90:91]
	global_load_dword v107, v[12:13], off nt
	global_load_dword v108, v[14:15], off nt
	global_load_dword v109, v[80:81], off nt
	global_load_dword v110, v[82:83], off nt
	global_load_dword v111, v[84:85], off nt
	global_load_dword v112, v[86:87], off nt
	s_nop 0
	global_load_dword v88, v[88:89], off nt
	s_nop 0
	global_load_dword v89, v[90:91], off nt
	v_lshlrev_b64 v[12:13], 12, v[6:7]
	v_or_b32_e32 v6, s20, v67
	v_lshlrev_b64 v[14:15], 12, v[6:7]
	v_or_b32_e32 v6, s20, v69
	v_lshlrev_b64 v[80:81], 12, v[6:7]
	v_or_b32_e32 v6, s20, v70
	v_lshlrev_b64 v[82:83], 12, v[6:7]
	v_or_b32_e32 v6, s20, v71
	v_lshlrev_b64 v[84:85], 12, v[6:7]
	v_or_b32_e32 v6, s20, v72
	v_lshl_add_u64 v[12:13], v[10:11], 0, v[12:13]
	v_lshl_add_u64 v[80:81], v[10:11], 0, v[80:81]
	v_lshl_add_u64 v[82:83], v[10:11], 0, v[82:83]
	v_lshlrev_b64 v[86:87], 12, v[6:7]
	v_or_b32_e32 v6, s20, v73
	v_lshl_add_u64 v[14:15], v[10:11], 0, v[14:15]
	v_lshl_add_u64 v[84:85], v[10:11], 0, v[84:85]
	v_lshl_add_u64 v[86:87], v[10:11], 0, v[86:87]
	global_load_dword v90, v[12:13], off nt
	global_load_dword v91, v[14:15], off nt
	s_nop 0
	global_load_dword v80, v[80:81], off nt
	s_nop 0
	global_load_dword v81, v[82:83], off nt
	s_nop 0
	global_load_dword v82, v[84:85], off nt
	global_load_dword v83, v[86:87], off nt
	v_lshlrev_b64 v[12:13], 12, v[6:7]
	v_or_b32_e32 v6, s20, v74
	v_lshlrev_b64 v[14:15], 12, v[6:7]
	v_lshl_add_u64 v[12:13], v[10:11], 0, v[12:13]
	v_lshl_add_u64 v[10:11], v[10:11], 0, v[14:15]
	global_load_dword v6, v[12:13], off nt
	s_nop 0
	global_load_dword v10, v[10:11], off nt
	s_waitcnt vmcnt(31)
; #define LAS __attribute__((address_space(3)))
; #define LDS_WAIT() asm volatile("s_waitcnt lgkmcnt(0)" ::: "memory")
; __device__ __forceinline__ unsigned pkbf(float lo, float hi) { typedef __bf16 bf2_t __attribute__((ext_vector_type(2))); f32x2 v = {lo, hi}; bf2_t b = __builtin_convertvector(v, bf2_t); return __builtin_bit_cast(unsigned, b); }
; __device__ __forceinline__ void tr_item(const float* W, int ldw, int K, int k0, int srccol0, bf16* WT, int dstrow0, const float* gain, float scale, LAS float* scr, int lane, const float* gain2 = nullptr) {
;     ...
;     for (int i = 0; i < 32; ++i) { const int kk = 2 * i + (lane >> 5); float gsc = gain ? gain[k0 + kk] * scale : scale; if (gain2) gsc *= gain2[k0 + kk]; scr[kk * 33 + (lane & 31)] = W[(size_t)(k0 + kk) * ldw + srccol0 + (lane & 31)] * gsc; }
;     LDS_WAIT();
;     const int c = lane & 7;
; #pragma unroll
;     for (int j = 0; j < 4; ++j) { const int n = (lane >> 3) + 8 * j; const LAS float* s = scr + (8 * c) * 33 + n;
;         u32x4 o; o.x = pkbf(s[0 * 33], s[1 * 33]); o.y = pkbf(s[2 * 33], s[3 * 33]); o.z = pkbf(s[4 * 33], s[5 * 33]); o.w = pkbf(s[6 * 33], s[7 * 33]);
;         *(u32x4*)(WT + (size_t)(dstrow0 + n) * K + k0 + 8 * c) = o; }
;     LDS_WAIT();
; __device__ __forceinline__ void phase_prep(const Args& a, unsigned char* ws, LAS unsigned char* lds, int vcu, int G, int tid, int wid, int lane) {
;     ...
;         if (r < I_D) { const int kb = r / 32, nb = r % 32; tr_item(a.in[5] + (size_t)l * FF * DM, DM, FF, kb * 64, nb * 32, (bf16*)(wl + WO_D1), nb * 32, nullptr, 0.5f, scr, lane); continue; }
	v_mul_f32_e32 v11, 0.5, v79
	v_add_u32_e32 v12, v5, v9
	s_waitcnt vmcnt(30)
	v_mul_f32_e32 v13, 0.5, v92
	ds_write2_b32 v12, v11, v13 offset1:66
	s_waitcnt vmcnt(29)
	v_mul_f32_e32 v11, 0.5, v93
	s_waitcnt vmcnt(28)
	v_mul_f32_e32 v13, 0.5, v94
	ds_write2_b32 v12, v11, v13 offset0:132 offset1:198
	s_waitcnt vmcnt(27)
	v_mul_f32_e32 v11, 0.5, v95
	s_waitcnt vmcnt(26)
	v_mul_f32_e32 v13, 0.5, v96
	v_add_u32_e32 v12, 0x400, v12
	ds_write2_b32 v12, v11, v13 offset0:8 offset1:74
	s_waitcnt vmcnt(25)
	v_mul_f32_e32 v11, 0.5, v97
	v_add_u32_e32 v12, v5, v24
	s_waitcnt vmcnt(24)
	v_mul_f32_e32 v13, 0.5, v98
	ds_write2_b32 v12, v11, v13 offset1:66
	s_lshl_b64 s[50:51], s[20:21], 1
	s_add_u32 s50, s46, s50
	s_addc_u32 s51, s45, s51
	s_waitcnt vmcnt(23)
	v_mul_f32_e32 v11, 0.5, v99
	s_waitcnt vmcnt(22)
	v_mul_f32_e32 v13, 0.5, v100
	ds_write2_b32 v12, v11, v13 offset0:132 offset1:198
	s_waitcnt vmcnt(21)
	v_mul_f32_e32 v11, 0.5, v101
	s_waitcnt vmcnt(20)
	v_mul_f32_e32 v13, 0.5, v102
	v_add_u32_e32 v12, 0x400, v12
	ds_write2_b32 v12, v11, v13 offset0:8 offset1:74
	s_waitcnt vmcnt(19)
	v_mul_f32_e32 v11, 0.5, v103
	v_add_u32_e32 v12, v5, v33
	s_waitcnt vmcnt(18)
	v_mul_f32_e32 v13, 0.5, v104
	ds_write2_b32 v12, v11, v13 offset1:66
	s_waitcnt vmcnt(17)
	v_mul_f32_e32 v11, 0.5, v105
	s_waitcnt vmcnt(16)
	v_mul_f32_e32 v13, 0.5, v106
	ds_write2_b32 v12, v11, v13 offset0:132 offset1:198
	v_add_u32_e32 v12, 0x400, v12
	s_waitcnt vmcnt(15)
	v_mul_f32_e32 v11, 0.5, v107
	s_waitcnt vmcnt(14)
	v_mul_f32_e32 v13, 0.5, v108
	ds_write2_b32 v12, v11, v13 offset0:8 offset1:74
	s_waitcnt vmcnt(13)
	v_mul_f32_e32 v11, 0.5, v109
	v_add_u32_e32 v12, v5, v42
	s_waitcnt vmcnt(12)
	v_mul_f32_e32 v13, 0.5, v110
	ds_write2_b32 v12, v11, v13 offset1:66
	s_waitcnt vmcnt(11)
	v_mul_f32_e32 v11, 0.5, v111
	s_waitcnt vmcnt(10)
	v_mul_f32_e32 v13, 0.5, v112
	ds_write2_b32 v12, v11, v13 offset0:132 offset1:198
	s_waitcnt vmcnt(9)
	v_mul_f32_e32 v11, 0.5, v88
	s_waitcnt vmcnt(8)
	v_mul_f32_e32 v13, 0.5, v89
	v_add_u32_e32 v12, 0x400, v12
	ds_write2_b32 v12, v11, v13 offset0:8 offset1:74
	v_add_u32_e32 v12, v5, v48
	s_waitcnt vmcnt(7)
	v_mul_f32_e32 v11, 0.5, v90
	s_waitcnt vmcnt(6)
	v_mul_f32_e32 v13, 0.5, v91
	ds_write2_b32 v12, v11, v13 offset1:66
	s_waitcnt vmcnt(5)
	v_mul_f32_e32 v11, 0.5, v80
	s_waitcnt vmcnt(4)
	v_mul_f32_e32 v13, 0.5, v81
	ds_write2_b32 v12, v11, v13 offset0:132 offset1:198
	s_waitcnt vmcnt(3)
	v_mul_f32_e32 v11, 0.5, v82
	s_waitcnt vmcnt(2)
	v_mul_f32_e32 v13, 0.5, v83
	v_add_u32_e32 v12, 0x400, v12
	ds_write2_b32 v12, v11, v13 offset0:8 offset1:74
	s_waitcnt vmcnt(1)
	v_mul_f32_e32 v6, 0.5, v6
	s_waitcnt vmcnt(0)
	v_mul_f32_e32 v10, 0.5, v10
	ds_write2_b32 v12, v6, v10 offset0:140 offset1:206
	s_waitcnt lgkmcnt(0)
	v_lshlrev_b32_e32 v6, 1, v8
	ds_read2_b32 v[14:15], v47 offset0:33 offset1:41
	ds_read2_b32 v[80:81], v47 offset1:8
	ds_read2_b32 v[82:83], v47 offset0:66 offset1:74
	ds_read2_b32 v[84:85], v47 offset0:99 offset1:107
	ds_read2_b32 v[86:87], v47 offset0:132 offset1:140
	ds_read2_b32 v[88:89], v47 offset0:165 offset1:173
	ds_read2_b32 v[90:91], v47 offset0:198 offset1:206
	ds_read2_b32 v[92:93], v47 offset0:231 offset1:239
	v_lshl_add_u64 v[10:11], s[50:51], 0, v[6:7]
	v_or_b32_e32 v6, s2, v46
	v_mul_u32_u24_e32 v6, 0xb00, v6
	v_lshl_add_u64 v[94:95], v[10:11], 0, s[40:41]
	v_lshlrev_b32_e32 v6, 1, v6
	v_lshl_add_u64 v[96:97], v[94:95], 0, v[6:7]
	v_or_b32_e32 v6, s2, v75
	s_waitcnt lgkmcnt(6)
	v_cvt_pk_bf16_f32 v10, v80, v14
	s_waitcnt lgkmcnt(4)
	v_cvt_pk_bf16_f32 v11, v82, v84
	s_waitcnt lgkmcnt(2)
	v_cvt_pk_bf16_f32 v12, v86, v88
	s_waitcnt lgkmcnt(0)
	v_cvt_pk_bf16_f32 v13, v90, v92
	v_mul_u32_u24_e32 v6, 0xb00, v6
	global_store_dwordx4 v[96:97], v[10:13], off
	v_lshlrev_b32_e32 v6, 1, v6
	s_nop 0
	v_cvt_pk_bf16_f32 v10, v81, v15
	v_cvt_pk_bf16_f32 v11, v83, v85
	v_cvt_pk_bf16_f32 v12, v87, v89
	v_cvt_pk_bf16_f32 v13, v91, v93
	v_lshl_add_u64 v[14:15], v[94:95], 0, v[6:7]
	ds_read2_b32 v[80:81], v47 offset0:16 offset1:24
	ds_read2_b32 v[82:83], v47 offset0:49 offset1:57
	ds_read2_b32 v[84:85], v47 offset0:82 offset1:90
	ds_read2_b32 v[86:87], v47 offset0:115 offset1:123
	ds_read2_b32 v[88:89], v47 offset0:148 offset1:156
	ds_read2_b32 v[90:91], v47 offset0:181 offset1:189
	ds_read2_b32 v[92:93], v47 offset0:214 offset1:222
	ds_read2_b32 v[96:97], v47 offset0:247 offset1:255
	v_or_b32_e32 v6, s2, v76
	v_mul_u32_u24_e32 v6, 0xb00, v6
	v_lshlrev_b32_e32 v6, 1, v6
	global_store_dwordx4 v[14:15], v[10:13], off
	v_lshl_add_u64 v[14:15], v[94:95], 0, v[6:7]
	v_or_b32_e32 v6, s2, v77
	v_mul_u32_u24_e32 v6, 0xb00, v6
	s_waitcnt lgkmcnt(6)
	v_cvt_pk_bf16_f32 v10, v80, v82
	s_waitcnt lgkmcnt(4)
	v_cvt_pk_bf16_f32 v11, v84, v86
	s_waitcnt lgkmcnt(2)
	v_cvt_pk_bf16_f32 v12, v88, v90
	s_waitcnt lgkmcnt(0)
	v_cvt_pk_bf16_f32 v13, v92, v96
	v_lshlrev_b32_e32 v6, 1, v6
	global_store_dwordx4 v[14:15], v[10:13], off
	v_lshl_add_u64 v[14:15], v[94:95], 0, v[6:7]
	s_nop 0
	v_cvt_pk_bf16_f32 v10, v81, v83
	v_cvt_pk_bf16_f32 v11, v85, v87
	v_cvt_pk_bf16_f32 v12, v89, v91
	v_cvt_pk_bf16_f32 v13, v93, v97
	global_store_dwordx4 v[14:15], v[10:13], off
	s_waitcnt lgkmcnt(0)

; __device__ __forceinline__ void tr_item(const float* W, int ldw, int K, int k0, int srccol0, bf16* WT, int dstrow0, const float* gain, float scale, LAS float* scr, int lane, const float* gain2 = nullptr) {
;     ...
;     for (int i = 0; i < 32; ++i) { const int kk = 2 * i + (lane >> 5); float gsc = gain ? gain[k0 + kk] * scale : scale; if (gain2) gsc *= gain2[k0 + kk]; scr[kk * 33 + (lane & 31)] = W[(size_t)(k0 + kk) * ldw + srccol0 + (lane & 31)] * gsc; }
; __device__ __forceinline__ void phase_prep(const Args& a, unsigned char* ws, LAS unsigned char* lds, int vcu, int G, int tid, int wid, int lane) {
;     ...
;             const int kb = r / 176, nb = r % 176, n0 = nb * 32, pn = n0 >> 8, half = (n0 >> 7) & 1, j0 = n0 & 127;
;             const float* src = a.in[second ? (half ? 18 : 17) : (half ? 4 : 3)] + (size_t)l * DM * FF;
;             tr_item(src, FF, DM, kb * 64, pn * 128 + j0, (bf16*)(wl + (second ? WO_GU2 : WO_GU1)), n0, a.in[second ? 16 : 2] + l * DM, 1.f, scr, lane, (!second && l > 0) ? a.in[20] + (l - 1) * DM : nullptr);
.LBB0_80:
	s_andn2_b64 vcc, exec, s[2:3]
	s_cbranch_vccnz .LBB0_13
	s_and_b64 s[2:3], s[42:43], exec
	s_cselect_b32 s2, s47, s48
	s_sext_i32_i16 s3, s2
	s_mulk_i32 s3, 0xba3
	s_lshr_b32 s5, s3, 31
	s_ashr_i32 s3, s3, 19
	s_add_i32 s5, s3, s5
	s_and_b64 s[48:49], s[42:43], exec
	s_cselect_b32 s3, 3, 17
	s_lshl_b32 s50, s5, 6
	s_and_b64 s[48:49], s[42:43], exec
	s_cselect_b32 s20, 16, 0x80
	s_add_u32 s48, s78, s20
	s_addc_u32 s49, s79, 0
	s_load_dwordx2 s[48:49], s[48:49], 0x0
	s_mulk_i32 s5, 0xb0
	s_sub_i32 s2, s2, s5
	s_sext_i32_i16 s5, s2
	s_bfe_u32 s2, s2, 0x10002
	s_add_i32 s2, s2, s3
	s_lshl_b32 s2, s2, 3
	s_load_dwordx2 s[2:3], s[78:79], s2 offset:0x0
	s_lshl_b32 s52, s4, 12
	s_lshl_b32 s53, s50, 2
	s_add_i32 s52, s52, s53
	s_add_u32 s56, s14, s53
	s_addc_u32 s57, s15, 0
	s_cmpk_gt_i32 s44, 0x29ff
	s_cselect_b64 s[58:59], -1, 0
	s_and_b64 s[58:59], s[58:59], s[42:43]
	s_and_b64 s[58:59], s[58:59], s[28:29]
	s_lshl_b32 s20, s5, 5
	s_and_b32 s47, s20, 0x60
	s_lshl_b32 s51, s5, 4
	s_and_b32 s51, s51, 0xffffff80
	s_or_b32 s51, s51, s47
	s_mul_i32 s47, s50, 0xb00
	s_add_i32 s51, s51, s47
	s_lshl_b32 s51, s51, 2
	s_mul_hi_i32 s47, s4, 0xb00000
	s_mul_i32 s4, s4, 0xb00000
	s_add_u32 s4, s4, s51
	s_addc_u32 s47, s47, 0
	s_waitcnt lgkmcnt(0)
	s_add_u32 s54, s2, s4
	s_addc_u32 s55, s3, s47
	s_add_u32 s52, s48, s52
	s_addc_u32 s53, s49, 0
	s_and_b64 s[2:3], s[42:43], exec
	s_cselect_b32 s2, 0, 0x1980000
	s_add_u32 s4, s46, s2
	s_addc_u32 s5, s45, 0
	s_lshl_b32 s2, s50, 1
	s_lshl_b32 s3, s20, 11
	s_add_i32 s2, s2, s3
	s_add_u32 s2, s4, s2
	s_addc_u32 s3, s5, 0
	v_mul_u32_u24_e32 v118, 0x2c00, v2
	v_lshlrev_b32_e32 v119, 2, v8
	v_lshl_add_u32 v118, v4, 2, v118
	s_nop 0
	global_load_dwordx4 v[152:155], v119, s[52:53]
	global_load_dwordx4 v[156:159], v119, s[52:53] offset:16
	s_cmp_lg_u64 s[58:59], 0
	s_cbranch_scc0 .Lprep_gu_nog2a
	global_load_dwordx4 v[160:163], v119, s[56:57]
	global_load_dwordx4 v[164:167], v119, s[56:57] offset:16
.Lprep_gu_nog2a:
	global_load_dword v120, v118, s[54:55] nt
	s_add_u32 s54, s54, 0x5800
	s_addc_u32 s55, s55, 0
	global_load_dword v121, v118, s[54:55] nt
	s_add_u32 s54, s54, 0x5800
	s_addc_u32 s55, s55, 0
	global_load_dword v122, v118, s[54:55] nt
	s_add_u32 s54, s54, 0x5800
	s_addc_u32 s55, s55, 0
	global_load_dword v123, v118, s[54:55] nt
	s_add_u32 s54, s54, 0x5800
	s_addc_u32 s55, s55, 0
	global_load_dword v124, v118, s[54:55] nt
	s_add_u32 s54, s54, 0x5800
	s_addc_u32 s55, s55, 0
	global_load_dword v125, v118, s[54:55] nt
	s_add_u32 s54, s54, 0x5800
	s_addc_u32 s55, s55, 0
	global_load_dword v126, v118, s[54:55] nt
	s_add_u32 s54, s54, 0x5800
	s_addc_u32 s55, s55, 0
	global_load_dword v127, v118, s[54:55] nt
	s_add_u32 s54, s54, 0x5800
	s_addc_u32 s55, s55, 0
	global_load_dword v128, v118, s[54:55] nt
	s_add_u32 s54, s54, 0x5800
	s_addc_u32 s55, s55, 0
	global_load_dword v129, v118, s[54:55] nt
	s_add_u32 s54, s54, 0x5800
	s_addc_u32 s55, s55, 0
	global_load_dword v130, v118, s[54:55] nt
	s_add_u32 s54, s54, 0x5800
	s_addc_u32 s55, s55, 0
	global_load_dword v131, v118, s[54:55] nt
	s_add_u32 s54, s54, 0x5800
	s_addc_u32 s55, s55, 0
	global_load_dword v132, v118, s[54:55] nt
	s_add_u32 s54, s54, 0x5800
	s_addc_u32 s55, s55, 0
	global_load_dword v133, v118, s[54:55] nt
	s_add_u32 s54, s54, 0x5800
	s_addc_u32 s55, s55, 0
	global_load_dword v134, v118, s[54:55] nt
	s_add_u32 s54, s54, 0x5800
	s_addc_u32 s55, s55, 0
	global_load_dword v135, v118, s[54:55] nt
	s_add_u32 s54, s54, 0x5800
	s_addc_u32 s55, s55, 0
	global_load_dword v136, v118, s[54:55] nt
	s_add_u32 s54, s54, 0x5800
	s_addc_u32 s55, s55, 0
	global_load_dword v137, v118, s[54:55] nt
	s_add_u32 s54, s54, 0x5800
	s_addc_u32 s55, s55, 0
	global_load_dword v138, v118, s[54:55] nt
	s_add_u32 s54, s54, 0x5800
	s_addc_u32 s55, s55, 0
	global_load_dword v139, v118, s[54:55] nt
	s_add_u32 s54, s54, 0x5800
	s_addc_u32 s55, s55, 0
	global_load_dword v140, v118, s[54:55] nt
	s_add_u32 s54, s54, 0x5800
	s_addc_u32 s55, s55, 0
	global_load_dword v141, v118, s[54:55] nt
	s_add_u32 s54, s54, 0x5800
	s_addc_u32 s55, s55, 0
	global_load_dword v142, v118, s[54:55] nt
	s_add_u32 s54, s54, 0x5800
	s_addc_u32 s55, s55, 0
	global_load_dword v143, v118, s[54:55] nt
	s_add_u32 s54, s54, 0x5800
	s_addc_u32 s55, s55, 0
	global_load_dword v144, v118, s[54:55] nt
	s_add_u32 s54, s54, 0x5800
	s_addc_u32 s55, s55, 0
	global_load_dword v145, v118, s[54:55] nt
	s_add_u32 s54, s54, 0x5800
	s_addc_u32 s55, s55, 0
	global_load_dword v146, v118, s[54:55] nt
	s_add_u32 s54, s54, 0x5800
	s_addc_u32 s55, s55, 0
	global_load_dword v147, v118, s[54:55] nt
	s_add_u32 s54, s54, 0x5800
	s_addc_u32 s55, s55, 0
	global_load_dword v148, v118, s[54:55] nt
	s_add_u32 s54, s54, 0x5800
	s_addc_u32 s55, s55, 0
	global_load_dword v149, v118, s[54:55] nt
	s_add_u32 s54, s54, 0x5800
	s_addc_u32 s55, s55, 0
	global_load_dword v150, v118, s[54:55] nt
	s_add_u32 s54, s54, 0x5800
	s_addc_u32 s55, s55, 0
	global_load_dword v151, v118, s[54:55] nt
	v_add_u32_e32 v119, v5, v9
	s_waitcnt vmcnt(28)
	ds_write_b32 v119, v120
	ds_write_b32 v119, v121 offset:264
	ds_write_b32 v119, v122 offset:528
	ds_write_b32 v119, v123 offset:792
	s_waitcnt vmcnt(24)
	ds_write_b32 v119, v124 offset:1056
	ds_write_b32 v119, v125 offset:1320
	ds_write_b32 v119, v126 offset:1584
	ds_write_b32 v119, v127 offset:1848
	s_waitcnt vmcnt(20)
	ds_write_b32 v119, v128 offset:2112
	ds_write_b32 v119, v129 offset:2376
	ds_write_b32 v119, v130 offset:2640
	ds_write_b32 v119, v131 offset:2904
	s_waitcnt vmcnt(16)
	ds_write_b32 v119, v132 offset:3168
	ds_write_b32 v119, v133 offset:3432
	ds_write_b32 v119, v134 offset:3696
	ds_write_b32 v119, v135 offset:3960
	s_waitcnt vmcnt(12)
	ds_write_b32 v119, v136 offset:4224
	ds_write_b32 v119, v137 offset:4488
	ds_write_b32 v119, v138 offset:4752
	ds_write_b32 v119, v139 offset:5016
	s_waitcnt vmcnt(8)
	ds_write_b32 v119, v140 offset:5280
	ds_write_b32 v119, v141 offset:5544
	ds_write_b32 v119, v142 offset:5808
	ds_write_b32 v119, v143 offset:6072
	s_waitcnt vmcnt(4)
	ds_write_b32 v119, v144 offset:6336
	ds_write_b32 v119, v145 offset:6600
	ds_write_b32 v119, v146 offset:6864
	ds_write_b32 v119, v147 offset:7128
	s_waitcnt vmcnt(0)
	ds_write_b32 v119, v148 offset:7392
	ds_write_b32 v119, v149 offset:7656
	ds_write_b32 v119, v150 offset:7920
	ds_write_b32 v119, v151 offset:8184
	s_cmp_lg_u64 s[58:59], 0
	s_cbranch_scc0 .Lprep_gu_nog2b
	v_pk_mul_f32 v[152:153], v[152:153], v[160:161]
	v_pk_mul_f32 v[154:155], v[154:155], v[162:163]
	v_pk_mul_f32 v[156:157], v[156:157], v[164:165]
	v_pk_mul_f32 v[158:159], v[158:159], v[166:167]

; __device__ __forceinline__ void phase_prep(const Args& a, unsigned char* ws, LAS unsigned char* lds, int vcu, int G, int tid, int wid, int lane) {
;     ...
;     for (int row0 = gw; row0 < T; row0 += 4 * NGW) {
;         f32x4 v[4][4]; float sq[4];
; #pragma unroll
;         for (int k = 0; k < 4; ++k) {
;             const int row = row0 + k * NGW;
;             if (row < T) {
;                 const float* xr = (row < TP) ? a.in[0] + (size_t)row * DM : a.in[1] + (size_t)(row - TP) * DM;
; #pragma unroll
;                 for (int j = 0; j < 4; ++j) v[k][j] = ((const f32x4*)xr)[lane + 64 * j];
;             }
;         }
.LBB0_232:
	s_add_i32 s8, s18, 0xffff8000
	s_ashr_i32 s19, s18, 31
	s_cmp_lt_i32 s18, 0x8000
	s_cselect_b32 s9, s19, 0
	s_cselect_b32 s8, s18, s8
	s_waitcnt lgkmcnt(0)
	s_cselect_b32 s10, s5, s7
	s_cselect_b32 s11, s4, s6
	s_lshl_b64 s[8:9], s[8:9], 12
	s_add_u32 s8, s11, s8
	s_addc_u32 s9, s10, s9
	global_load_dwordx4 v[62:65], v68, s[8:9] nt
	global_load_dwordx4 v[58:61], v68, s[8:9] offset:1024 nt
	global_load_dwordx4 v[54:57], v68, s[8:9] offset:2048 nt
	global_load_dwordx4 v[50:53], v68, s[8:9] offset:3072 nt
	s_add_i32 s8, s18, s64
	s_cmp_lt_i32 s8, 0x18000
	s_cselect_b64 s[22:23], -1, 0
	s_cmp_gt_i32 s8, 0x17fff
	s_cbranch_scc1 .LBB0_234
	s_ashr_i32 s9, s8, 31
	s_add_i32 s10, s8, 0xffff8000
	s_cmp_lt_i32 s8, 0x8000
	s_cselect_b32 s11, s9, 0
	s_cselect_b32 s10, s8, s10
	s_cselect_b32 s9, s5, s7
	s_cselect_b32 s12, s4, s6
	s_lshl_b64 s[10:11], s[10:11], 12
	s_add_u32 s10, s12, s10
	s_addc_u32 s11, s9, s11
	global_load_dwordx4 v[46:49], v68, s[10:11] nt
	global_load_dwordx4 v[42:45], v68, s[10:11] offset:1024 nt
	global_load_dwordx4 v[38:41], v68, s[10:11] offset:2048 nt
	global_load_dwordx4 v[34:37], v68, s[10:11] offset:3072 nt
.LBB0_234:
	s_add_i32 s12, s26, s18
	s_cmp_lt_i32 s12, 0x18000
	s_cselect_b64 s[20:21], -1, 0
	s_cmp_gt_i32 s12, 0x17fff
	s_cbranch_scc1 .LBB0_236
	s_ashr_i32 s9, s12, 31
	s_add_i32 s10, s12, 0xffff8000
	s_cmp_lt_i32 s12, 0x8000
	s_cselect_b32 s11, s9, 0
	s_cselect_b32 s10, s12, s10
	s_cselect_b32 s9, s5, s7
	s_cselect_b32 s13, s4, s6
	s_lshl_b64 s[10:11], s[10:11], 12
	s_add_u32 s10, s13, s10
	s_addc_u32 s11, s9, s11
	global_load_dwordx4 v[30:33], v68, s[10:11] nt
	global_load_dwordx4 v[26:29], v68, s[10:11] offset:1024 nt
	global_load_dwordx4 v[22:25], v68, s[10:11] offset:2048 nt
	global_load_dwordx4 v[18:21], v68, s[10:11] offset:3072 nt
.LBB0_236:
	s_add_i32 s10, s27, s18
	s_cmp_lt_i32 s10, 0x18000
	s_cselect_b64 s[14:15], -1, 0
	s_cmp_gt_i32 s10, 0x17fff
	s_cbranch_scc1 .LBB0_238
	s_ashr_i32 s9, s10, 31
	s_add_i32 s11, s10, 0xffff8000
	s_cmp_lt_i32 s10, 0x8000
	s_cselect_b32 s25, s9, 0
	s_cselect_b32 s24, s10, s11
	s_cselect_b32 s9, s5, s7
	s_cselect_b32 s11, s4, s6
	s_lshl_b64 s[24:25], s[24:25], 12
	s_add_u32 s24, s11, s24
	s_addc_u32 s25, s9, s25
	global_load_dwordx4 v[14:17], v68, s[24:25] nt
	global_load_dwordx4 v[10:13], v68, s[24:25] offset:1024 nt
	global_load_dwordx4 v[6:9], v68, s[24:25] offset:2048 nt
	global_load_dwordx4 v[2:5], v68, s[24:25] offset:3072 nt

; __device__ __forceinline__ void ret_gammas(const Args& a, int l, int h, float& lgf2, float& lgb2) {
;     const float xf = a.in[8][(l * 2 + 0) * 4 + h], xb = a.in[8][(l * 2 + 1) * 4 + h];
;     lgf2 = -log1pf(expf(-xf)) * LOG2E; lgb2 = -log1pf(expf(-xb)) * LOG2E;
; __device__ __forceinline__ void phase_scan(const Args& a, unsigned char* ws, bf16* STB, int l, int vcu, int G, int tid, int z) {
;     ...
;     for (int it = gt; it < 192 * 2 * 2048; it += NT) {
;         const int grp = it & 2047, dir = (it >> 11) & 1, bh = it >> 12, h = bh & 3;
;         float lgf2, lgb2; ret_gammas(a, l, h, lgf2, lgb2);
;         const float g = __builtin_amdgcn_exp2f(128.f * (dir ? lgb2 : lgf2));
;         bf16* base = ST + ((size_t)(bh * 16) * 2 + dir) * 16384 + grp * 8;
;         u32x4 kv[16];
;         const size_t cst = (size_t)(32768 + z);
; #pragma unroll
;         for (int n = 0; n < 16; ++n) kv[n] = *(const u32x4*)(base + (size_t)n * cst);
.LBB0_562:
	v_lshl_add_u32 v74, s3, 9, v0
	s_mov_b32 s0, 0xc0000
	v_cmp_gt_i32_e32 vcc, s0, v74
	s_and_saveexec_b64 s[4:5], vcc
	s_cbranch_execz .LBB0_565
	s_load_dwordx2 s[8:9], s[78:79], 0xa8
	s_load_dwordx2 s[6:7], s[78:79], 0x40
	s_ashr_i32 s0, s2, 31
	v_lshlrev_b32_e32 v0, 3, v0
	v_mov_b32_e32 v65, 0
	s_waitcnt lgkmcnt(0)
	s_add_u32 s8, s8, s2
	s_addc_u32 s9, s9, s0
	s_add_i32 s10, s2, 0x8000
	s_ashr_i32 s11, s10, 31
	s_lshl_b32 s0, s1, 9
	s_lshl_b64 s[12:13], s[10:11], 1
	v_lshl_add_u32 v75, s3, 12, v0
	s_lshl_b32 s1, s1, 12
	s_mov_b64 s[14:15], 0
	s_mov_b32 s16, 0xbfb8aa3b
	s_mov_b32 s17, 0x42ce8ed0
	s_mov_b32 s18, 0xc2b17218
	s_mov_b32 s19, 0x7f800000
	v_mov_b32_e32 v76, 0x7f800000
	s_mov_b32 s20, 0x3f2aaaab
	v_mov_b32_e32 v77, 0x3ecc95a3
	s_mov_b32 s21, 0x3f317218
	s_mov_b32 s100, 1
	s_and_b32 s101, s0, 0x3fff
	s_mov_b32 s22, 0x33800000
	v_mov_b32_e32 v80, v65
	v_mov_b32_e32 v81, v65
	v_mov_b32_e32 v82, v65
	v_mov_b32_e32 v83, v65
	s_mov_b32 s23, 0xbffff
	v_mov_b32_e32 v66, 0x3f317218
.LBB0_564:
	v_ashrrev_i32_e32 v1, 12, v74
	v_lshlrev_b32_e32 v3, 2, v1
	v_and_b32_e32 v3, 12, v3
	global_load_dword v67, v3, s[6:7]
	global_load_dword v79, v3, s[6:7] offset:16
	v_lshlrev_b32_e32 v4, 4, v1
	v_ashrrev_i32_e32 v5, 31, v4
	v_bfe_u32 v78, v74, 11, 1
	v_lshlrev_b64 v[4:5], 16, v[4:5]
	v_and_b32_e32 v2, 0x3ff8, v75
	v_lshlrev_b32_e32 v0, 15, v78
	v_lshl_add_u64 v[4:5], s[8:9], 0, v[4:5]
	v_lshl_add_u32 v0, v2, 1, v0
	v_add_co_u32_e32 v72, vcc, v4, v0
	v_addc_co_u32_e32 v73, vcc, 0, v5, vcc
	v_lshl_add_u64 v[4:5], s[10:11], 1, v[72:73]
	v_lshl_add_u64 v[12:13], v[4:5], 0, s[12:13]
	v_bfe_i32 v0, v74, 11, 1
	v_lshl_add_u64 v[14:15], v[12:13], 0, s[12:13]
	v_and_b32_e32 v0, 15, v0
	v_add_u32_e32 v6, 7, v78
	v_sub_u32_e32 v8, 8, v78
	v_lshl_add_u64 v[16:17], v[14:15], 0, s[12:13]
	v_mad_i64_i32 v[0:1], s[2:3], v0, s10, 0
	v_mad_i64_i32 v[6:7], s[2:3], v6, s10, 0
	v_mad_i64_i32 v[8:9], s[2:3], v8, s10, 0
	v_lshl_add_u64 v[18:19], v[16:17], 0, s[12:13]
	v_lshl_add_u64 v[84:85], v[0:1], 1, v[72:73]
	v_lshl_add_u64 v[70:71], v[6:7], 1, v[72:73]
	v_lshl_add_u64 v[68:69], v[8:9], 1, v[72:73]
	global_load_dwordx4 v[56:59], v[72:73], off
	global_load_dwordx4 v[0:3], v[4:5], off
	s_nop 0
	global_load_dwordx4 v[4:7], v[12:13], off
	global_load_dwordx4 v[8:11], v[14:15], off
	s_nop 0
	global_load_dwordx4 v[12:15], v[16:17], off
	global_load_dwordx4 v[20:23], v[18:19], off
	v_lshl_add_u64 v[16:17], v[18:19], 0, s[12:13]
	global_load_dwordx4 v[32:35], v[16:17], off
	v_lshl_add_u64 v[16:17], v[16:17], 0, s[12:13]
	global_load_dwordx4 v[48:51], v[16:17], off
	v_lshl_add_u64 v[16:17], v[16:17], 0, s[12:13]
	global_load_dwordx4 v[52:55], v[16:17], off
	v_lshl_add_u64 v[16:17], v[16:17], 0, s[12:13]
	global_load_dwordx4 v[44:47], v[16:17], off
	v_lshl_add_u64 v[16:17], v[16:17], 0, s[12:13]
	global_load_dwordx4 v[40:43], v[16:17], off
	v_lshl_add_u64 v[16:17], v[16:17], 0, s[12:13]
	global_load_dwordx4 v[36:39], v[16:17], off
	v_lshl_add_u64 v[16:17], v[16:17], 0, s[12:13]
	global_load_dwordx4 v[28:31], v[16:17], off
	v_lshl_add_u64 v[16:17], v[16:17], 0, s[12:13]
	v_lshl_add_u64 v[60:61], v[16:17], 0, s[12:13]
	global_load_dwordx4 v[24:27], v[16:17], off
	v_add_u32_e32 v74, s0, v74
	global_load_dwordx4 v[16:19], v[60:61], off
	v_lshl_add_u64 v[60:61], v[60:61], 0, s[12:13]
	global_load_dwordx4 v[60:63], v[60:61], off
	v_cmp_lt_i32_e32 vcc, s23, v74
	global_store_dwordx4 v[84:85], v[80:83], off
	s_or_b64 s[14:15], vcc, s[14:15]
	v_add_u32_e32 v75, s1, v75
	s_cmp_eq_u32 s100, 0
	s_cbranch_scc1 .Lscan_gskip_0
	s_waitcnt vmcnt(17)
	v_mul_f32_e32 v64, 0xbfb8aa3b, v67
	v_mul_f32_e32 v84, 0xbfb8aa3b, v79
	v_fma_f32 v85, v67, s16, -v64
	v_rndne_f32_e32 v86, v64
	v_fma_f32 v87, v79, s16, -v84
	v_rndne_f32_e32 v88, v84
	v_fmac_f32_e32 v85, 0xb2a5705f, v67
	v_sub_f32_e32 v64, v64, v86
	v_fmac_f32_e32 v87, 0xb2a5705f, v79
	v_sub_f32_e32 v84, v84, v88
	v_add_f32_e32 v64, v64, v85
	v_cvt_i32_f32_e32 v86, v86
	v_add_f32_e32 v84, v84, v87
	v_exp_f32_e32 v64, v64
	v_cvt_i32_f32_e32 v88, v88
	v_exp_f32_e32 v84, v84
	v_cmp_nlt_f32_e64 s[2:3], s17, v67
	v_ldexp_f32 v64, v64, v86
	v_cmp_nlt_f32_e32 vcc, s17, v79
	v_ldexp_f32 v84, v84, v88
	v_cndmask_b32_e64 v64, 0, v64, s[2:3]
	v_cmp_ngt_f32_e64 s[2:3], s18, v67
	v_cndmask_b32_e32 v84, 0, v84, vcc
	v_cmp_ngt_f32_e32 vcc, s18, v79
	v_cndmask_b32_e64 v64, v76, v64, s[2:3]
	v_add_f32_e32 v67, 1.0, v64
	v_cndmask_b32_e32 v79, v76, v84, vcc
	v_add_f32_e32 v88, 1.0, v79
	v_add_f32_e32 v89, -1.0, v67
	v_frexp_mant_f32_e32 v90, v67
	v_cvt_f64_f32_e32 v[84:85], v67
	v_add_f32_e32 v91, -1.0, v88
	v_frexp_mant_f32_e32 v92, v88
	v_cvt_f64_f32_e32 v[86:87], v88
	v_sub_f32_e32 v93, v89, v67
	v_frexp_exp_i32_f64_e32 v84, v[84:85]
	v_cmp_gt_f32_e32 vcc, s20, v90
	v_sub_f32_e32 v89, v64, v89
	v_sub_f32_e32 v85, v91, v88
	v_frexp_exp_i32_f64_e32 v86, v[86:87]
	v_cmp_gt_f32_e64 s[2:3], s20, v92
	v_add_f32_e32 v87, 1.0, v93
	v_subbrev_co_u32_e32 v84, vcc, 0, v84, vcc
	v_sub_f32_e32 v90, v79, v91
	v_add_f32_e32 v85, 1.0, v85
	v_subbrev_co_u32_e64 v86, vcc, 0, v86, s[2:3]
	v_add_f32_e32 v87, v89, v87
	v_sub_u32_e32 v89, 0, v84
	v_add_f32_e32 v85, v90, v85
	v_sub_u32_e32 v90, 0, v86
	v_ldexp_f32 v67, v67, v89
	v_ldexp_f32 v88, v88, v90
	v_ldexp_f32 v85, v85, v90
	v_add_f32_e32 v90, -1.0, v67
	v_add_f32_e32 v92, 1.0, v67
	v_ldexp_f32 v87, v87, v89
	v_add_f32_e32 v93, -1.0, v88
	v_add_f32_e32 v94, 1.0, v88
	v_add_f32_e32 v89, 1.0, v90
	v_add_f32_e32 v91, -1.0, v92
	v_add_f32_e32 v95, 1.0, v93
	v_add_f32_e32 v96, -1.0, v94
	v_sub_f32_e32 v89, v67, v89
	v_sub_f32_e32 v67, v67, v91
	v_sub_f32_e32 v91, v88, v95
	v_sub_f32_e32 v88, v88, v96
; __device__ __forceinline__ void ret_gammas(const Args& a, int l, int h, float& lgf2, float& lgb2) {
;     const float xf = a.in[8][(l * 2 + 0) * 4 + h], xb = a.in[8][(l * 2 + 1) * 4 + h];
;     lgf2 = -log1pf(expf(-xf)) * LOG2E; lgb2 = -log1pf(expf(-xb)) * LOG2E;
; __device__ __forceinline__ void phase_scan(const Args& a, unsigned char* ws, bf16* STB, int l, int vcu, int G, int tid, int z) {
;     ...
;         float lgf2, lgb2; ret_gammas(a, l, h, lgf2, lgb2);
;         const float g = __builtin_amdgcn_exp2f(128.f * (dir ? lgb2 : lgf2));
	v_add_f32_e32 v67, v87, v67
	v_add_f32_e32 v95, v87, v89
	v_add_f32_e32 v87, v85, v91
	v_add_f32_e32 v85, v85, v88
	v_add_f32_e32 v100, v92, v67
	v_add_f32_e32 v101, v94, v85
	v_rcp_f32_e32 v102, v100
	v_rcp_f32_e32 v103, v101
	v_add_f32_e32 v89, v90, v95
	v_add_f32_e32 v91, v93, v87
	v_sub_f32_e32 v88, v92, v100
	v_sub_f32_e32 v92, v94, v101
	v_mul_f32_e32 v105, v89, v102
	v_add_f32_e32 v85, v85, v92
	v_mul_f32_e32 v106, v91, v103
	v_mul_f32_e32 v92, v100, v105
	v_add_f32_e32 v67, v67, v88
	v_mul_f32_e32 v94, v101, v106
	v_fma_f32 v96, v105, v100, -v92
	v_fma_f32 v98, v106, v101, -v94
	v_fmac_f32_e32 v96, v105, v67
	v_sub_f32_e32 v90, v90, v89
	v_sub_f32_e32 v93, v93, v91
	v_fmac_f32_e32 v98, v106, v85
	v_add_f32_e32 v88, v92, v96
	v_add_f32_e32 v104, v95, v90
	v_add_f32_e32 v87, v87, v93
	v_add_f32_e32 v90, v94, v98
	v_sub_f32_e32 v93, v89, v88
	v_mov_b32_e32 v97, v88
	v_sub_f32_e32 v95, v91, v90
	v_pk_add_f32 v[88:89], v[88:89], v[92:93] neg_lo:[0,1] neg_hi:[0,1]
	v_mov_b32_e32 v99, v90
	v_pk_add_f32 v[90:91], v[90:91], v[94:95] neg_lo:[0,1] neg_hi:[0,1]
	v_pk_add_f32 v[88:89], v[88:89], v[96:97] neg_lo:[0,1] neg_hi:[0,1]
	v_pk_add_f32 v[90:91], v[90:91], v[98:99] neg_lo:[0,1] neg_hi:[0,1]
	v_add_f32_e32 v89, v104, v89
	v_add_f32_e32 v87, v87, v91
	v_add_f32_e32 v88, v88, v89
	v_add_f32_e32 v87, v90, v87
	v_add_f32_e32 v89, v93, v88
	v_add_f32_e32 v91, v95, v87
	v_mul_f32_e32 v90, v102, v89
	v_mul_f32_e32 v97, v103, v91
	v_mul_f32_e32 v92, v100, v90
	v_sub_f32_e32 v93, v93, v89
	v_add_f32_e32 v107, v105, v90
	v_mul_f32_e32 v94, v101, v97
	v_fma_f32 v96, v90, v100, -v92
	v_add_f32_e32 v104, v88, v93
	v_add_f32_e32 v108, v106, v97
	v_sub_f32_e32 v88, v107, v105
	v_fma_f32 v98, v97, v101, -v94
	v_fmac_f32_e32 v96, v90, v67
	v_sub_f32_e32 v93, v108, v106
	v_sub_f32_e32 v67, v90, v88
	v_fmac_f32_e32 v98, v97, v85
	v_add_f32_e32 v88, v92, v96
	v_sub_f32_e32 v95, v95, v91
	v_sub_f32_e32 v85, v97, v93
	v_add_f32_e32 v90, v94, v98
	v_sub_f32_e32 v93, v89, v88
	v_add_f32_e32 v87, v87, v95
	v_mov_b32_e32 v97, v88
	v_sub_f32_e32 v95, v91, v90
	v_pk_add_f32 v[88:89], v[88:89], v[92:93] neg_lo:[0,1] neg_hi:[0,1]
	v_mov_b32_e32 v99, v90
	v_pk_add_f32 v[90:91], v[90:91], v[94:95] neg_lo:[0,1] neg_hi:[0,1]
	v_pk_add_f32 v[88:89], v[88:89], v[96:97] neg_lo:[0,1] neg_hi:[0,1]
	v_pk_add_f32 v[90:91], v[90:91], v[98:99] neg_lo:[0,1] neg_hi:[0,1]
	v_add_f32_e32 v89, v104, v89
	v_add_f32_e32 v87, v87, v91
	v_add_f32_e32 v88, v88, v89
	v_add_f32_e32 v87, v90, v87
	v_add_f32_e32 v88, v93, v88
	v_add_f32_e32 v87, v95, v87
	v_mul_f32_e32 v88, v102, v88
	v_mul_f32_e32 v87, v103, v87
	v_add_f32_e32 v67, v67, v88
	v_cvt_f32_i32_e32 v84, v84
	v_add_f32_e32 v87, v85, v87
	v_add_f32_e32 v85, v107, v67
	v_cvt_f32_i32_e32 v86, v86
	v_add_f32_e32 v88, v108, v87
	v_mul_f32_e32 v90, v85, v85
	v_sub_f32_e32 v92, v85, v107
	v_mul_f32_e32 v94, v88, v88
	v_sub_f32_e32 v93, v88, v108
	v_fmamk_f32 v95, v90, 0x3e9b6dac, v77
	v_ldexp_f32 v89, v85, 1
	v_sub_f32_e32 v92, v67, v92
	v_mul_f32_e32 v85, v85, v90
	v_fmamk_f32 v96, v94, 0x3e9b6dac, v77
	v_sub_f32_e32 v93, v87, v93
	v_fmaak_f32 v67, v90, v95, 0x3f2aaada
	v_mul_f32_e32 v87, v88, v94
	v_ldexp_f32 v95, v92, 1
	v_ldexp_f32 v104, v93, 1
	v_pk_mul_f32 v[92:93], v[84:85], v[66:67]
	v_fmaak_f32 v67, v94, v96, 0x3f2aaada
	v_ldexp_f32 v91, v88, 1
	v_fma_f32 v88, v84, s21, -v92
	v_pk_mul_f32 v[96:97], v[86:87], v[66:67]
	v_fmac_f32_e32 v88, 0xb102e308, v84
	v_fma_f32 v90, v86, s21, -v96
	v_pk_add_f32 v[98:99], v[92:93], v[88:89]
	v_fmac_f32_e32 v90, 0xb102e308, v86
	v_sub_f32_e32 v67, v99, v89
	v_pk_add_f32 v[102:103], v[96:97], v[90:91]
	v_sub_f32_e32 v67, v93, v67
	v_sub_f32_e32 v85, v103, v91
	v_mov_b32_e32 v94, v92
	v_add_f32_e32 v95, v95, v67
	v_sub_f32_e32 v67, v97, v85
	v_mov_b32_e32 v84, v96
	v_pk_add_f32 v[86:87], v[98:99], v[92:93] neg_lo:[0,1] neg_hi:[0,1]
	v_pk_add_f32 v[92:93], v[102:103], v[96:97] neg_lo:[0,1] neg_hi:[0,1]
	v_pk_add_f32 v[96:97], v[98:99], v[94:95]
	v_add_f32_e32 v85, v104, v67
	v_mov_b32_e32 v89, v98
	v_mov_b32_e32 v87, v97
	v_pk_add_f32 v[106:107], v[102:103], v[84:85]
	v_mov_b32_e32 v91, v102
	v_mov_b32_e32 v104, v85
	v_pk_add_f32 v[84:85], v[88:89], v[86:87] neg_lo:[0,1] neg_hi:[0,1]
	v_pk_add_f32 v[86:87], v[88:89], v[86:87]
	v_mov_b32_e32 v93, v107
	v_pk_add_f32 v[108:109], v[86:87], v[98:99] op_sel:[1,0] op_sel_hi:[0,1] neg_lo:[0,1] neg_hi:[0,1]
	v_pk_add_f32 v[110:111], v[90:91], v[92:93] neg_lo:[0,1] neg_hi:[0,1]
	v_pk_add_f32 v[90:91], v[90:91], v[92:93]
	v_mov_b32_e32 v101, v98
	v_mov_b32_e32 v100, v95
	v_mov_b32_e32 v94, v97
	v_mov_b32_e32 v95, v87
	v_pk_add_f32 v[92:93], v[96:97], v[108:109] op_sel_hi:[1,0] neg_lo:[0,1] neg_hi:[0,1]
	v_pk_mov_b32 v[96:97], v[98:99], v[108:109] op_sel:[1,0]
	v_pk_add_f32 v[98:99], v[90:91], v[102:103] op_sel:[1,0] op_sel_hi:[0,1] neg_lo:[0,1] neg_hi:[0,1]
	v_mov_b32_e32 v88, v107
	v_mov_b32_e32 v89, v91
	v_pk_add_f32 v[94:95], v[94:95], v[96:97] neg_lo:[0,1] neg_hi:[0,1]
	v_pk_add_f32 v[96:97], v[106:107], v[98:99] op_sel_hi:[1,0] neg_lo:[0,1] neg_hi:[0,1]
	v_pk_mov_b32 v[98:99], v[102:103], v[98:99] op_sel:[1,0]
	v_mov_b32_e32 v105, v102
	v_mov_b32_e32 v92, v84
	v_pk_add_f32 v[94:95], v[100:101], v[94:95] neg_lo:[0,1] neg_hi:[0,1]
	v_pk_add_f32 v[88:89], v[88:89], v[98:99] neg_lo:[0,1] neg_hi:[0,1]
	v_mov_b32_e32 v96, v110
	v_pk_add_f32 v[92:93], v[92:93], v[94:95]
	v_pk_add_f32 v[88:89], v[104:105], v[88:89] neg_lo:[0,1] neg_hi:[0,1]
	v_pk_add_f32 v[98:99], v[92:93], v[92:93] op_sel:[0,1] op_sel_hi:[1,0]
	v_pk_add_f32 v[96:97], v[96:97], v[88:89]
	v_mov_b32_e32 v85, v87
	v_pk_add_f32 v[86:87], v[86:87], v[98:99] op_sel:[1,0] op_sel_hi:[0,1]
	v_mov_b32_e32 v95, v98
	v_pk_add_f32 v[98:99], v[96:97], v[96:97] op_sel:[0,1] op_sel_hi:[1,0]
	v_mov_b32_e32 v111, v91
	v_mov_b32_e32 v93, v86
	v_pk_add_f32 v[90:91], v[90:91], v[98:99] op_sel:[1,0] op_sel_hi:[0,1]
	v_mov_b32_e32 v89, v98
	v_pk_add_f32 v[98:99], v[92:93], v[84:85] neg_lo:[0,1] neg_hi:[0,1]
	v_mov_b32_e32 v97, v90
	v_sub_f32_e32 v67, v92, v98
	v_pk_add_f32 v[92:93], v[96:97], v[110:111] neg_lo:[0,1] neg_hi:[0,1]
	v_pk_add_f32 v[94:95], v[94:95], v[98:99] neg_lo:[0,1] neg_hi:[0,1]
	v_sub_f32_e32 v67, v84, v67
	v_sub_f32_e32 v87, v96, v92
	v_pk_add_f32 v[84:85], v[88:89], v[92:93] neg_lo:[0,1] neg_hi:[0,1]
	v_add_f32_e32 v67, v94, v67
	v_sub_f32_e32 v87, v110, v87
	v_add_f32_e32 v67, v67, v95
	v_add_f32_e32 v84, v84, v87
	v_add_f32_e32 v67, v86, v67
	v_add_f32_e32 v84, v84, v85
	v_cmp_neq_f32_e32 vcc, s19, v64
	v_add_f32_e32 v84, v90, v84
	v_cmp_lt_f32_e64 s[2:3], |v64|, s22
	v_cndmask_b32_e32 v67, v76, v67, vcc
	v_cmp_neq_f32_e32 vcc, s19, v79
	v_cndmask_b32_e64 v64, v67, v64, s[2:3]
	s_nop 0
	v_cndmask_b32_e32 v67, v76, v84, vcc
	v_cmp_lt_f32_e64 vcc, |v79|, s22
	s_nop 1
	v_cndmask_b32_e32 v67, v67, v79, vcc
	v_cmp_eq_u32_e32 vcc, 0, v78
	s_nop 1
	v_cndmask_b32_e32 v64, v67, v64, vcc
	v_mul_f32_e32 v64, 0xbfb8aa3b, v64
	v_mul_f32_e32 v64, 0x43000000, v64
	v_exp_f32_e32 v64, v64
	s_mov_b32 s100, s101

; __device__ __forceinline__ void ret_gammas(const Args& a, int l, int h, float& lgf2, float& lgb2) {
;     const float xf = a.in[8][(l * 2 + 0) * 4 + h], xb = a.in[8][(l * 2 + 1) * 4 + h];
;     lgf2 = -log1pf(expf(-xf)) * LOG2E; lgb2 = -log1pf(expf(-xb)) * LOG2E;
; __device__ __forceinline__ void phase_scan(const Args& a, unsigned char* ws, bf16* STB, int l, int vcu, int G, int tid, int z) {
;     ...
;     for (int it = gt; it < 192 * 2 * 2048; it += NT) {
;         const int grp = it & 2047, dir = (it >> 11) & 1, bh = it >> 12, h = bh & 3;
;         float lgf2, lgb2; ret_gammas(a, l, h, lgf2, lgb2);
;         const float g = __builtin_amdgcn_exp2f(128.f * (dir ? lgb2 : lgf2));
;         bf16* base = ST + ((size_t)(bh * 16) * 2 + dir) * 16384 + grp * 8;
;         u32x4 kv[16];
;         const size_t cst = (size_t)(32768 + z);
; #pragma unroll
;         for (int n = 0; n < 16; ++n) kv[n] = *(const u32x4*)(base + (size_t)n * cst);
.LBB0_1292:
	v_ashrrev_i32_e32 v1, 12, v74
	v_lshlrev_b32_e32 v3, 2, v1
	v_and_b32_e32 v3, 12, v3
	global_load_dword v67, v3, s[6:7] offset:32
	global_load_dword v79, v3, s[6:7] offset:48
	v_lshlrev_b32_e32 v4, 4, v1
	v_ashrrev_i32_e32 v5, 31, v4
	v_bfe_u32 v78, v74, 11, 1
	v_lshlrev_b64 v[4:5], 16, v[4:5]
	v_and_b32_e32 v2, 0x3ff8, v75
	v_lshlrev_b32_e32 v0, 15, v78
	v_lshl_add_u64 v[4:5], s[8:9], 0, v[4:5]
	v_lshl_add_u32 v0, v2, 1, v0
	v_add_co_u32_e32 v72, vcc, v4, v0
	v_addc_co_u32_e32 v73, vcc, 0, v5, vcc
	v_lshl_add_u64 v[4:5], s[10:11], 1, v[72:73]
	v_lshl_add_u64 v[12:13], v[4:5], 0, s[12:13]
	v_bfe_i32 v0, v74, 11, 1
	v_lshl_add_u64 v[14:15], v[12:13], 0, s[12:13]
	v_and_b32_e32 v0, 15, v0
	v_add_u32_e32 v6, 7, v78
	v_sub_u32_e32 v8, 8, v78
	v_lshl_add_u64 v[16:17], v[14:15], 0, s[12:13]
	v_mad_i64_i32 v[0:1], s[2:3], v0, s10, 0
	v_mad_i64_i32 v[6:7], s[2:3], v6, s10, 0
	v_mad_i64_i32 v[8:9], s[2:3], v8, s10, 0
	v_lshl_add_u64 v[18:19], v[16:17], 0, s[12:13]
	v_lshl_add_u64 v[84:85], v[0:1], 1, v[72:73]
	v_lshl_add_u64 v[70:71], v[6:7], 1, v[72:73]
	v_lshl_add_u64 v[68:69], v[8:9], 1, v[72:73]
	global_load_dwordx4 v[56:59], v[72:73], off
	global_load_dwordx4 v[0:3], v[4:5], off
	s_nop 0
	global_load_dwordx4 v[4:7], v[12:13], off
	global_load_dwordx4 v[8:11], v[14:15], off
	s_nop 0
	global_load_dwordx4 v[12:15], v[16:17], off
	global_load_dwordx4 v[20:23], v[18:19], off
	v_lshl_add_u64 v[16:17], v[18:19], 0, s[12:13]
	global_load_dwordx4 v[32:35], v[16:17], off
	v_lshl_add_u64 v[16:17], v[16:17], 0, s[12:13]
	global_load_dwordx4 v[48:51], v[16:17], off
	v_lshl_add_u64 v[16:17], v[16:17], 0, s[12:13]
	global_load_dwordx4 v[52:55], v[16:17], off
	v_lshl_add_u64 v[16:17], v[16:17], 0, s[12:13]
	global_load_dwordx4 v[44:47], v[16:17], off
	v_lshl_add_u64 v[16:17], v[16:17], 0, s[12:13]
	global_load_dwordx4 v[40:43], v[16:17], off
	v_lshl_add_u64 v[16:17], v[16:17], 0, s[12:13]
	global_load_dwordx4 v[36:39], v[16:17], off
	v_lshl_add_u64 v[16:17], v[16:17], 0, s[12:13]
	global_load_dwordx4 v[28:31], v[16:17], off
	v_lshl_add_u64 v[16:17], v[16:17], 0, s[12:13]
	v_lshl_add_u64 v[60:61], v[16:17], 0, s[12:13]
	global_load_dwordx4 v[24:27], v[16:17], off
	v_add_u32_e32 v74, s0, v74
	global_load_dwordx4 v[16:19], v[60:61], off
	v_lshl_add_u64 v[60:61], v[60:61], 0, s[12:13]
	global_load_dwordx4 v[60:63], v[60:61], off
	v_cmp_lt_i32_e32 vcc, s23, v74
	global_store_dwordx4 v[84:85], v[80:83], off
	s_or_b64 s[14:15], vcc, s[14:15]
	v_add_u32_e32 v75, s1, v75
	s_cmp_eq_u32 s100, 0
	s_cbranch_scc1 .Lscan_gskip_1
	s_waitcnt vmcnt(17)
	v_mul_f32_e32 v64, 0xbfb8aa3b, v67
	v_mul_f32_e32 v84, 0xbfb8aa3b, v79
	v_fma_f32 v85, v67, s16, -v64
	v_rndne_f32_e32 v86, v64
	v_fma_f32 v87, v79, s16, -v84
	v_rndne_f32_e32 v88, v84
	v_fmac_f32_e32 v85, 0xb2a5705f, v67
	v_sub_f32_e32 v64, v64, v86
	v_fmac_f32_e32 v87, 0xb2a5705f, v79
	v_sub_f32_e32 v84, v84, v88
	v_add_f32_e32 v64, v64, v85
	v_cvt_i32_f32_e32 v86, v86
	v_add_f32_e32 v84, v84, v87
	v_exp_f32_e32 v64, v64
	v_cvt_i32_f32_e32 v88, v88
	v_exp_f32_e32 v84, v84
	v_cmp_nlt_f32_e64 s[2:3], s17, v67
	v_ldexp_f32 v64, v64, v86
	v_cmp_nlt_f32_e32 vcc, s17, v79
	v_ldexp_f32 v84, v84, v88
	v_cndmask_b32_e64 v64, 0, v64, s[2:3]
	v_cmp_ngt_f32_e64 s[2:3], s18, v67
	v_cndmask_b32_e32 v84, 0, v84, vcc
	v_cmp_ngt_f32_e32 vcc, s18, v79
	v_cndmask_b32_e64 v64, v76, v64, s[2:3]
	v_add_f32_e32 v67, 1.0, v64
	v_cndmask_b32_e32 v79, v76, v84, vcc
	v_add_f32_e32 v88, 1.0, v79
	v_add_f32_e32 v89, -1.0, v67
	v_frexp_mant_f32_e32 v90, v67
	v_cvt_f64_f32_e32 v[84:85], v67
	v_add_f32_e32 v91, -1.0, v88
	v_frexp_mant_f32_e32 v92, v88
	v_cvt_f64_f32_e32 v[86:87], v88
	v_sub_f32_e32 v93, v89, v67
	v_frexp_exp_i32_f64_e32 v84, v[84:85]
	v_cmp_gt_f32_e32 vcc, s20, v90
	v_sub_f32_e32 v89, v64, v89
	v_sub_f32_e32 v85, v91, v88
	v_frexp_exp_i32_f64_e32 v86, v[86:87]
	v_cmp_gt_f32_e64 s[2:3], s20, v92
	v_add_f32_e32 v87, 1.0, v93
	v_subbrev_co_u32_e32 v84, vcc, 0, v84, vcc
	v_sub_f32_e32 v90, v79, v91
	v_add_f32_e32 v85, 1.0, v85
	v_subbrev_co_u32_e64 v86, vcc, 0, v86, s[2:3]
	v_add_f32_e32 v87, v89, v87
	v_sub_u32_e32 v89, 0, v84
	v_add_f32_e32 v85, v90, v85
	v_sub_u32_e32 v90, 0, v86
	v_ldexp_f32 v67, v67, v89
	v_ldexp_f32 v88, v88, v90
	v_ldexp_f32 v85, v85, v90
	v_add_f32_e32 v90, -1.0, v67
	v_add_f32_e32 v92, 1.0, v67
	v_ldexp_f32 v87, v87, v89
	v_add_f32_e32 v93, -1.0, v88
	v_add_f32_e32 v94, 1.0, v88
	v_add_f32_e32 v89, 1.0, v90
	v_add_f32_e32 v91, -1.0, v92
	v_add_f32_e32 v95, 1.0, v93
	v_add_f32_e32 v96, -1.0, v94
	v_sub_f32_e32 v89, v67, v89
	v_sub_f32_e32 v67, v67, v91
	v_sub_f32_e32 v91, v88, v95
	v_sub_f32_e32 v88, v88, v96
	v_add_f32_e32 v67, v87, v67
	v_add_f32_e32 v95, v87, v89
	v_add_f32_e32 v87, v85, v91
	v_add_f32_e32 v85, v85, v88
	v_add_f32_e32 v100, v92, v67
	v_add_f32_e32 v101, v94, v85
	v_rcp_f32_e32 v102, v100
	v_rcp_f32_e32 v103, v101
	v_add_f32_e32 v89, v90, v95
	v_add_f32_e32 v91, v93, v87
	v_sub_f32_e32 v88, v92, v100
	v_sub_f32_e32 v92, v94, v101
	v_mul_f32_e32 v105, v89, v102
	v_add_f32_e32 v85, v85, v92
	v_mul_f32_e32 v106, v91, v103
	v_mul_f32_e32 v92, v100, v105
	v_add_f32_e32 v67, v67, v88
	v_mul_f32_e32 v94, v101, v106
	v_fma_f32 v96, v105, v100, -v92
	v_fma_f32 v98, v106, v101, -v94
	v_fmac_f32_e32 v96, v105, v67
	v_sub_f32_e32 v90, v90, v89
	v_sub_f32_e32 v93, v93, v91
	v_fmac_f32_e32 v98, v106, v85
	v_add_f32_e32 v88, v92, v96
	v_add_f32_e32 v104, v95, v90
	v_add_f32_e32 v87, v87, v93
	v_add_f32_e32 v90, v94, v98
	v_sub_f32_e32 v93, v89, v88
	v_mov_b32_e32 v97, v88
	v_sub_f32_e32 v95, v91, v90
	v_pk_add_f32 v[88:89], v[88:89], v[92:93] neg_lo:[0,1] neg_hi:[0,1]
	v_mov_b32_e32 v99, v90
; __device__ __forceinline__ void ret_gammas(const Args& a, int l, int h, float& lgf2, float& lgb2) {
;     const float xf = a.in[8][(l * 2 + 0) * 4 + h], xb = a.in[8][(l * 2 + 1) * 4 + h];
;     lgf2 = -log1pf(expf(-xf)) * LOG2E; lgb2 = -log1pf(expf(-xb)) * LOG2E;
; __device__ __forceinline__ void phase_scan(const Args& a, unsigned char* ws, bf16* STB, int l, int vcu, int G, int tid, int z) {
;     ...
;         float lgf2, lgb2; ret_gammas(a, l, h, lgf2, lgb2);
;         const float g = __builtin_amdgcn_exp2f(128.f * (dir ? lgb2 : lgf2));
	v_pk_add_f32 v[90:91], v[90:91], v[94:95] neg_lo:[0,1] neg_hi:[0,1]
	v_pk_add_f32 v[88:89], v[88:89], v[96:97] neg_lo:[0,1] neg_hi:[0,1]
	v_pk_add_f32 v[90:91], v[90:91], v[98:99] neg_lo:[0,1] neg_hi:[0,1]
	v_add_f32_e32 v89, v104, v89
	v_add_f32_e32 v87, v87, v91
	v_add_f32_e32 v88, v88, v89
	v_add_f32_e32 v87, v90, v87
	v_add_f32_e32 v89, v93, v88
	v_add_f32_e32 v91, v95, v87
	v_mul_f32_e32 v90, v102, v89
	v_mul_f32_e32 v97, v103, v91
	v_mul_f32_e32 v92, v100, v90
	v_sub_f32_e32 v93, v93, v89
	v_add_f32_e32 v107, v105, v90
	v_mul_f32_e32 v94, v101, v97
	v_fma_f32 v96, v90, v100, -v92
	v_add_f32_e32 v104, v88, v93
	v_add_f32_e32 v108, v106, v97
	v_sub_f32_e32 v88, v107, v105
	v_fma_f32 v98, v97, v101, -v94
	v_fmac_f32_e32 v96, v90, v67
	v_sub_f32_e32 v93, v108, v106
	v_sub_f32_e32 v67, v90, v88
	v_fmac_f32_e32 v98, v97, v85
	v_add_f32_e32 v88, v92, v96
	v_sub_f32_e32 v95, v95, v91
	v_sub_f32_e32 v85, v97, v93
	v_add_f32_e32 v90, v94, v98
	v_sub_f32_e32 v93, v89, v88
	v_add_f32_e32 v87, v87, v95
	v_mov_b32_e32 v97, v88
	v_sub_f32_e32 v95, v91, v90
	v_pk_add_f32 v[88:89], v[88:89], v[92:93] neg_lo:[0,1] neg_hi:[0,1]
	v_mov_b32_e32 v99, v90
	v_pk_add_f32 v[90:91], v[90:91], v[94:95] neg_lo:[0,1] neg_hi:[0,1]
	v_pk_add_f32 v[88:89], v[88:89], v[96:97] neg_lo:[0,1] neg_hi:[0,1]
	v_pk_add_f32 v[90:91], v[90:91], v[98:99] neg_lo:[0,1] neg_hi:[0,1]
	v_add_f32_e32 v89, v104, v89
	v_add_f32_e32 v87, v87, v91
	v_add_f32_e32 v88, v88, v89
	v_add_f32_e32 v87, v90, v87
	v_add_f32_e32 v88, v93, v88
	v_add_f32_e32 v87, v95, v87
	v_mul_f32_e32 v88, v102, v88
	v_mul_f32_e32 v87, v103, v87
	v_add_f32_e32 v67, v67, v88
	v_cvt_f32_i32_e32 v84, v84
	v_add_f32_e32 v87, v85, v87
	v_add_f32_e32 v85, v107, v67
	v_cvt_f32_i32_e32 v86, v86
	v_add_f32_e32 v88, v108, v87
	v_mul_f32_e32 v90, v85, v85
	v_sub_f32_e32 v92, v85, v107
	v_mul_f32_e32 v94, v88, v88
	v_sub_f32_e32 v93, v88, v108
	v_fmamk_f32 v95, v90, 0x3e9b6dac, v77
	v_ldexp_f32 v89, v85, 1
	v_sub_f32_e32 v92, v67, v92
	v_mul_f32_e32 v85, v85, v90
	v_fmamk_f32 v96, v94, 0x3e9b6dac, v77
	v_sub_f32_e32 v93, v87, v93
	v_fmaak_f32 v67, v90, v95, 0x3f2aaada
	v_mul_f32_e32 v87, v88, v94
	v_ldexp_f32 v95, v92, 1
	v_ldexp_f32 v104, v93, 1
	v_pk_mul_f32 v[92:93], v[84:85], v[66:67]
	v_fmaak_f32 v67, v94, v96, 0x3f2aaada
	v_ldexp_f32 v91, v88, 1
	v_fma_f32 v88, v84, s21, -v92
	v_pk_mul_f32 v[96:97], v[86:87], v[66:67]
	v_fmac_f32_e32 v88, 0xb102e308, v84
	v_fma_f32 v90, v86, s21, -v96
	v_pk_add_f32 v[98:99], v[92:93], v[88:89]
	v_fmac_f32_e32 v90, 0xb102e308, v86
	v_sub_f32_e32 v67, v99, v89
	v_pk_add_f32 v[102:103], v[96:97], v[90:91]
	v_sub_f32_e32 v67, v93, v67
	v_sub_f32_e32 v85, v103, v91
	v_mov_b32_e32 v94, v92
	v_add_f32_e32 v95, v95, v67
	v_sub_f32_e32 v67, v97, v85
	v_mov_b32_e32 v84, v96
	v_pk_add_f32 v[86:87], v[98:99], v[92:93] neg_lo:[0,1] neg_hi:[0,1]
	v_pk_add_f32 v[92:93], v[102:103], v[96:97] neg_lo:[0,1] neg_hi:[0,1]
	v_pk_add_f32 v[96:97], v[98:99], v[94:95]
	v_add_f32_e32 v85, v104, v67
	v_mov_b32_e32 v89, v98
	v_mov_b32_e32 v87, v97
	v_pk_add_f32 v[106:107], v[102:103], v[84:85]
	v_mov_b32_e32 v91, v102
	v_mov_b32_e32 v104, v85
	v_pk_add_f32 v[84:85], v[88:89], v[86:87] neg_lo:[0,1] neg_hi:[0,1]
	v_pk_add_f32 v[86:87], v[88:89], v[86:87]
	v_mov_b32_e32 v93, v107
	v_pk_add_f32 v[108:109], v[86:87], v[98:99] op_sel:[1,0] op_sel_hi:[0,1] neg_lo:[0,1] neg_hi:[0,1]
	v_pk_add_f32 v[110:111], v[90:91], v[92:93] neg_lo:[0,1] neg_hi:[0,1]
	v_pk_add_f32 v[90:91], v[90:91], v[92:93]
	v_mov_b32_e32 v101, v98
	v_mov_b32_e32 v100, v95
	v_mov_b32_e32 v94, v97
	v_mov_b32_e32 v95, v87
	v_pk_add_f32 v[92:93], v[96:97], v[108:109] op_sel_hi:[1,0] neg_lo:[0,1] neg_hi:[0,1]
	v_pk_mov_b32 v[96:97], v[98:99], v[108:109] op_sel:[1,0]
	v_pk_add_f32 v[98:99], v[90:91], v[102:103] op_sel:[1,0] op_sel_hi:[0,1] neg_lo:[0,1] neg_hi:[0,1]
	v_mov_b32_e32 v88, v107
	v_mov_b32_e32 v89, v91
	v_pk_add_f32 v[94:95], v[94:95], v[96:97] neg_lo:[0,1] neg_hi:[0,1]
	v_pk_add_f32 v[96:97], v[106:107], v[98:99] op_sel_hi:[1,0] neg_lo:[0,1] neg_hi:[0,1]
	v_pk_mov_b32 v[98:99], v[102:103], v[98:99] op_sel:[1,0]
	v_mov_b32_e32 v105, v102
	v_mov_b32_e32 v92, v84
	v_pk_add_f32 v[94:95], v[100:101], v[94:95] neg_lo:[0,1] neg_hi:[0,1]
	v_pk_add_f32 v[88:89], v[88:89], v[98:99] neg_lo:[0,1] neg_hi:[0,1]
	v_mov_b32_e32 v96, v110
	v_pk_add_f32 v[92:93], v[92:93], v[94:95]
	v_pk_add_f32 v[88:89], v[104:105], v[88:89] neg_lo:[0,1] neg_hi:[0,1]
	v_pk_add_f32 v[98:99], v[92:93], v[92:93] op_sel:[0,1] op_sel_hi:[1,0]
	v_pk_add_f32 v[96:97], v[96:97], v[88:89]
	v_mov_b32_e32 v85, v87
	v_pk_add_f32 v[86:87], v[86:87], v[98:99] op_sel:[1,0] op_sel_hi:[0,1]
	v_mov_b32_e32 v95, v98
	v_pk_add_f32 v[98:99], v[96:97], v[96:97] op_sel:[0,1] op_sel_hi:[1,0]
	v_mov_b32_e32 v111, v91
	v_mov_b32_e32 v93, v86
	v_pk_add_f32 v[90:91], v[90:91], v[98:99] op_sel:[1,0] op_sel_hi:[0,1]
	v_mov_b32_e32 v89, v98
	v_pk_add_f32 v[98:99], v[92:93], v[84:85] neg_lo:[0,1] neg_hi:[0,1]
	v_mov_b32_e32 v97, v90
	v_sub_f32_e32 v67, v92, v98
	v_pk_add_f32 v[92:93], v[96:97], v[110:111] neg_lo:[0,1] neg_hi:[0,1]
	v_pk_add_f32 v[94:95], v[94:95], v[98:99] neg_lo:[0,1] neg_hi:[0,1]
	v_sub_f32_e32 v67, v84, v67
	v_sub_f32_e32 v87, v96, v92
	v_pk_add_f32 v[84:85], v[88:89], v[92:93] neg_lo:[0,1] neg_hi:[0,1]
	v_add_f32_e32 v67, v94, v67
	v_sub_f32_e32 v87, v110, v87
	v_add_f32_e32 v67, v67, v95
	v_add_f32_e32 v84, v84, v87
	v_add_f32_e32 v67, v86, v67
	v_add_f32_e32 v84, v84, v85
	v_cmp_neq_f32_e32 vcc, s19, v64
	v_add_f32_e32 v84, v90, v84
	v_cmp_lt_f32_e64 s[2:3], |v64|, s22
	v_cndmask_b32_e32 v67, v76, v67, vcc
	v_cmp_neq_f32_e32 vcc, s19, v79
	v_cndmask_b32_e64 v64, v67, v64, s[2:3]
	s_nop 0
	v_cndmask_b32_e32 v67, v76, v84, vcc
	v_cmp_lt_f32_e64 vcc, |v79|, s22
	s_nop 1
	v_cndmask_b32_e32 v67, v67, v79, vcc
	v_cmp_eq_u32_e32 vcc, 0, v78
	s_nop 1
	v_cndmask_b32_e32 v64, v67, v64, vcc
	v_mul_f32_e32 v64, 0xbfb8aa3b, v64
	v_mul_f32_e32 v64, 0x43000000, v64
	v_exp_f32_e32 v64, v64
	s_mov_b32 s100, s101
